# w_in GEMM epilogue: rope-table loads (4 per row group) and rmsnorm-gain / lower-bound loads of the first row group issued together with counted vmcnt instead of load+vmcnt(0) one at a time
# speedup vs baseline: 1.0066x; 1.0066x over previous
.LBB0_958:
	s_and_b64 vcc, exec, s[0:1]
	s_cbranch_vccz .LBB0_974
	v_mul_f32_e32 v0, v127, v127
	v_fmac_f32_e32 v0, v126, v126
	v_fmac_f32_e32 v0, v128, v128
	v_fmac_f32_e32 v0, v129, v129
	v_fmac_f32_e32 v0, v122, v122
	v_fmac_f32_e32 v0, v123, v123
	v_fmac_f32_e32 v0, v124, v124
	v_fmac_f32_e32 v0, v125, v125
	v_fmac_f32_e32 v0, v118, v118
	v_fmac_f32_e32 v0, v119, v119
	v_pk_mul_f32 v[130:131], v[120:121], v[120:121]
	v_pk_mul_f32 v[132:133], v[114:115], v[114:115]
	v_add_f32_e32 v0, v130, v0
	v_add_f32_e32 v0, v131, v0
	v_add_f32_e32 v0, v132, v0
	v_pk_mul_f32 v[130:131], v[116:117], v[116:117]
	v_add_f32_e32 v0, v133, v0
	v_add_f32_e32 v0, v130, v0
	v_add_f32_e32 v0, v131, v0
	v_and_b32_e32 v131, 64, v214
	v_xor_b32_e32 v130, 16, v214
	v_add_u32_e32 v131, 64, v131
	v_cmp_lt_i32_e32 vcc, v130, v131
	s_and_b64 s[0:1], s[42:43], exec
	s_cselect_b32 s1, s18, s20
	v_cndmask_b32_e32 v130, v214, v130, vcc
	v_lshlrev_b32_e32 v130, 2, v130
	ds_bpermute_b32 v130, v130, v0
	s_cselect_b32 s0, s17, s19
	s_lshr_b32 s6, s28, 2
	s_and_b32 s6, s6, 0x7f0
	v_lshlrev_b32_e32 v207, 2, v138
	global_load_dwordx4 v[224:227], v207, s[0:1]
	global_load_dwordx4 v[228:231], v207, s[0:1] offset:64
	global_load_dwordx4 v[232:235], v207, s[0:1] offset:128
	global_load_dwordx4 v[236:239], v207, s[0:1] offset:192
	v_cmp_gt_i32_e32 vcc, s81, v156
	s_cbranch_vccz .Lrope_skip_0
	s_lshr_b32 s6, s28, 2
	s_and_b32 s6, s6, 0x7f0
	v_or_b32_e32 v157, s6, v167
	v_lshlrev_b32_e32 v157, 3, v157
	v_readlane_b32 s30, v254, 6
	v_readlane_b32 s31, v254, 7
	s_nop 4
	global_load_dwordx4 v[192:195], v157, s[30:31]
	global_load_dwordx4 v[196:199], v157, s[30:31] offset:64
	global_load_dwordx4 v[200:203], v[140:141], off
	global_load_dwordx4 v[204:207], v[140:141], off offset:64
.Lrope_skip_0:
	s_waitcnt lgkmcnt(0)
	v_add_f32_e32 v0, v0, v130
	v_xor_b32_e32 v130, 32, v214
	v_cmp_lt_i32_e32 vcc, v130, v131
	v_or_b32_e32 v131, s6, v167
	v_lshlrev_b32_e32 v157, 3, v131
	v_cndmask_b32_e32 v130, v214, v130, vcc
	v_lshlrev_b32_e32 v130, 2, v130
	ds_bpermute_b32 v130, v130, v0
	v_cmp_gt_i32_e32 vcc, s81, v156
	s_waitcnt lgkmcnt(0)
	v_add_f32_e32 v0, v0, v130
	v_fmamk_f32 v0, v0, 0x3c800000, v208
	v_rsq_f32_e32 v130, v0
	v_lshlrev_b32_e32 v0, 2, v138
	v_pk_mul_f32 v[132:133], v[126:127], v[130:131] op_sel_hi:[1,0]
	s_waitcnt vmcnt(3)
	v_mov_b64_e32 v[158:159], v[224:225]
	v_mov_b64_e32 v[160:161], v[226:227]
	v_pk_mul_f32 v[132:133], v[158:159], v[132:133]
	v_pk_mul_f32 v[158:159], v[128:129], v[130:131] op_sel_hi:[1,0]
	s_nop 0
	v_pk_mul_f32 v[162:163], v[160:161], v[158:159]
	s_and_saveexec_b64 s[6:7], vcc
	s_cbranch_execz .LBB0_961
	s_waitcnt vmcnt(3)
	v_mov_b64_e32 v[158:159], v[192:193]
	v_mov_b64_e32 v[160:161], v[194:195]
	v_pk_mul_f32 v[172:173], v[132:133], v[158:159] op_sel:[1,1] op_sel_hi:[1,0]
	v_pk_mul_f32 v[164:165], v[132:133], v[158:159]
	v_pk_fma_f32 v[132:133], v[132:133], v[158:159], v[172:173] op_sel_hi:[0,1,1]
	v_mul_f32_e32 v132, v163, v161
	v_pk_fma_f32 v[158:159], v[162:163], v[160:161], v[132:133] op_sel_hi:[1,1,0] neg_lo:[0,0,1] neg_hi:[0,0,1]
	v_mul_f32_e32 v132, v163, v160
	v_pk_fma_f32 v[160:161], v[162:163], v[160:161], v[132:133] op_sel:[0,1,0] op_sel_hi:[1,0,0]
	v_sub_f32_e32 v132, v164, v172
	v_mov_b32_e32 v162, v158
	v_mov_b32_e32 v163, v160
.LBB0_961:
	s_or_b64 exec, exec, s[6:7]
	v_lshl_add_u64 v[158:159], s[0:1], 0, v[0:1]
	v_readlane_b32 s0, v254, 35
	v_readlane_b32 s1, v254, 36
	v_pk_mul_f32 v[172:173], v[154:155], v[132:133]
	v_lshlrev_b32_e32 v0, 1, v138
	v_mov_b64_e32 v[160:161], s[0:1]
	v_mad_i64_i32 v[160:161], s[0:1], v156, s52, v[160:161]
	s_lshl_b32 s0, s27, 1
	s_mov_b32 s1, s35
	v_lshl_add_u64 v[160:161], v[160:161], 0, s[0:1]
	v_lshl_add_u64 v[164:165], s[76:77], 1, v[160:161]
	v_mov_b32_e32 v160, v154
	v_mov_b32_e32 v161, v154
	v_pk_mul_f32 v[162:163], v[160:161], v[162:163]
	v_lshl_add_u64 v[132:133], v[164:165], 0, v[0:1]
	v_cvt_pk_bf16_f32 v240, v172, v173
	v_cvt_pk_bf16_f32 v241, v162, v163
	v_mov_b32_e32 v131, v130
	v_pk_mul_f32 v[172:173], v[122:123], v[130:131]
	s_waitcnt vmcnt(2)
	v_mov_b64_e32 v[162:163], v[228:229]
	v_mov_b64_e32 v[164:165], v[230:231]
	v_pk_mul_f32 v[162:163], v[172:173], v[162:163]
	v_pk_mul_f32 v[172:173], v[124:125], v[130:131]
	s_nop 0
	v_pk_mul_f32 v[164:165], v[172:173], v[164:165]
	s_and_saveexec_b64 s[0:1], vcc
	s_cbranch_execz .LBB0_963
	s_waitcnt vmcnt(2)
	v_mov_b64_e32 v[172:173], v[196:197]
	v_mov_b64_e32 v[174:175], v[198:199]
	v_pk_mul_f32 v[178:179], v[162:163], v[172:173] op_sel:[1,1] op_sel_hi:[1,0]
	v_mul_f32_e32 v0, v165, v175
	v_pk_mul_f32 v[176:177], v[162:163], v[172:173]
	v_pk_fma_f32 v[162:163], v[162:163], v[172:173], v[178:179] op_sel_hi:[0,1,1]
	v_pk_fma_f32 v[172:173], v[164:165], v[174:175], v[0:1] op_sel_hi:[1,1,0] neg_lo:[0,0,1] neg_hi:[0,0,1]
	v_mul_f32_e32 v0, v165, v174
	v_pk_fma_f32 v[174:175], v[164:165], v[174:175], v[0:1] op_sel:[0,1,0] op_sel_hi:[1,0,0]
	v_sub_f32_e32 v162, v176, v178
	v_mov_b32_e32 v164, v172
	v_mov_b32_e32 v165, v174
.LBB0_963:
	s_or_b64 exec, exec, s[0:1]
	v_pk_mul_f32 v[160:161], v[160:161], v[164:165]
	v_pk_mul_f32 v[162:163], v[154:155], v[162:163]
	v_pk_mul_f32 v[164:165], v[118:119], v[130:131]
	v_cvt_pk_bf16_f32 v242, v162, v163
	v_cvt_pk_bf16_f32 v243, v160, v161
	s_waitcnt vmcnt(1)
	v_mov_b64_e32 v[160:161], v[232:233]
	v_mov_b64_e32 v[162:163], v[234:235]
	v_pk_mul_f32 v[160:161], v[164:165], v[160:161]
	v_pk_mul_f32 v[164:165], v[120:121], v[130:131]
	s_nop 0
	v_pk_mul_f32 v[164:165], v[164:165], v[162:163]
	s_and_saveexec_b64 s[0:1], vcc
	s_cbranch_execz .LBB0_965
	s_waitcnt vmcnt(1)
	v_mov_b64_e32 v[172:173], v[200:201]
	v_mov_b64_e32 v[174:175], v[202:203]
	v_pk_mul_f32 v[176:177], v[160:161], v[172:173] op_sel:[1,1] op_sel_hi:[1,0]
	v_mul_f32_e32 v0, v165, v175
	v_pk_mul_f32 v[162:163], v[160:161], v[172:173]
	v_pk_fma_f32 v[160:161], v[160:161], v[172:173], v[176:177] op_sel_hi:[0,1,1]
	v_pk_fma_f32 v[172:173], v[164:165], v[174:175], v[0:1] op_sel_hi:[1,1,0] neg_lo:[0,0,1] neg_hi:[0,0,1]
	v_mul_f32_e32 v0, v165, v174
	v_pk_fma_f32 v[174:175], v[164:165], v[174:175], v[0:1] op_sel:[0,1,0] op_sel_hi:[1,0,0]
	v_sub_f32_e32 v160, v162, v176
	v_mov_b32_e32 v164, v172
	v_mov_b32_e32 v165, v174
.LBB0_965:
	s_or_b64 exec, exec, s[0:1]
	v_mov_b32_e32 v162, v154
	v_mov_b32_e32 v163, v154
	v_pk_mul_f32 v[164:165], v[162:163], v[164:165]
	v_pk_mul_f32 v[160:161], v[154:155], v[160:161]
	v_pk_mul_f32 v[172:173], v[116:117], v[130:131]
	v_cvt_pk_bf16_f32 v244, v160, v161
	v_cvt_pk_bf16_f32 v245, v164, v165
	v_pk_mul_f32 v[164:165], v[114:115], v[130:131]
	s_waitcnt vmcnt(0)
	v_mov_b64_e32 v[158:159], v[236:237]
	v_mov_b64_e32 v[160:161], v[238:239]
	v_pk_mul_f32 v[130:131], v[164:165], v[158:159]
	v_pk_mul_f32 v[158:159], v[172:173], v[160:161]
	s_and_saveexec_b64 s[0:1], vcc
	s_cbranch_execz .LBB0_967
	s_waitcnt vmcnt(0)
	v_mov_b64_e32 v[172:173], v[204:205]
	v_mov_b64_e32 v[174:175], v[206:207]
	v_pk_mul_f32 v[164:165], v[130:131], v[172:173] op_sel:[1,1] op_sel_hi:[1,0]
	v_mul_f32_e32 v0, v159, v175
	v_pk_mul_f32 v[160:161], v[130:131], v[172:173]
	v_pk_fma_f32 v[130:131], v[130:131], v[172:173], v[164:165] op_sel_hi:[0,1,1]
	v_pk_fma_f32 v[172:173], v[158:159], v[174:175], v[0:1] op_sel_hi:[1,1,0] neg_lo:[0,0,1] neg_hi:[0,0,1]
	v_mul_f32_e32 v0, v159, v174
	v_pk_fma_f32 v[174:175], v[158:159], v[174:175], v[0:1] op_sel:[0,1,0] op_sel_hi:[1,0,0]
	v_sub_f32_e32 v130, v160, v164
	v_mov_b32_e32 v158, v172
	v_mov_b32_e32 v159, v174

.LBB0_989:
	s_and_b64 vcc, exec, s[0:1]
	s_cbranch_vccz .LBB0_991
	s_and_b64 s[0:1], s[68:69], exec
	v_readlane_b32 s0, v254, 25
	v_readlane_b32 s6, v254, 29
	v_readlane_b32 s1, v254, 26
	v_readlane_b32 s7, v254, 30
	v_ashrrev_i32_e32 v157, 31, v156
	s_cselect_b32 s1, s1, s7
	s_cselect_b32 s0, s0, s6
	v_lshlrev_b64 v[130:131], 10, v[156:157]
	v_lshl_add_u64 v[130:131], s[0:1], 0, v[130:131]
	s_lshl_b32 s0, s25, 2
	s_mov_b32 s1, s35
	v_lshl_add_u64 v[132:133], v[130:131], 0, s[0:1]
	v_lshl_add_u64 v[130:131], s[36:37], 2, v[148:149]
	global_load_dwordx4 v[224:227], v[130:131], off offset:-1024
	global_load_dwordx4 v[228:231], v[130:131], off offset:-960
	global_load_dwordx4 v[232:235], v[130:131], off offset:-896
	global_load_dwordx4 v[236:239], v[130:131], off offset:-832
	v_mul_f32_e32 v0, 0xbfb8aa3b, v126
	v_exp_f32_e32 v0, v0
	s_waitcnt vmcnt(3)
	s_nop 1
	v_mov_b64_e32 v[156:157], v[224:225]
	v_mov_b64_e32 v[158:159], v[226:227]
	v_sub_f32_e32 v161, 1.0, v157
	v_add_f32_e32 v0, 1.0, v0
	v_rcp_f32_e32 v126, v0
	v_mul_f32_e32 v0, 0xbfb8aa3b, v127
	v_exp_f32_e32 v0, v0
	v_sub_f32_e32 v160, 1.0, v156
	v_sub_f32_e32 v163, 1.0, v159
	v_sub_f32_e32 v162, 1.0, v158
	v_add_f32_e32 v0, 1.0, v0
	v_rcp_f32_e32 v127, v0
	v_mul_f32_e32 v0, 0xbfb8aa3b, v128
	v_exp_f32_e32 v0, v0
	v_pk_fma_f32 v[156:157], v[126:127], v[160:161], v[156:157]
	v_add_f32_e32 v0, 1.0, v0
	v_rcp_f32_e32 v128, v0
	v_mul_f32_e32 v0, 0xbfb8aa3b, v129
	v_exp_f32_e32 v0, v0
	s_nop 0
	v_add_f32_e32 v0, 1.0, v0
	v_rcp_f32_e32 v129, v0
	v_lshlrev_b32_e32 v0, 2, v138
	v_lshl_add_u64 v[126:127], v[132:133], 0, v[0:1]
	v_mul_f32_e32 v0, 0xbfb8aa3b, v122
	v_pk_fma_f32 v[158:159], v[128:129], v[162:163], v[158:159]
	global_store_dwordx4 v[126:127], v[156:159], off
	v_exp_f32_e32 v0, v0
	s_waitcnt vmcnt(3)
	s_nop 1
	v_mov_b64_e32 v[156:157], v[228:229]
	v_mov_b64_e32 v[158:159], v[230:231]
	v_sub_f32_e32 v129, 1.0, v157
	v_add_f32_e32 v0, 1.0, v0
	v_rcp_f32_e32 v122, v0
	v_mul_f32_e32 v0, 0xbfb8aa3b, v123
	v_exp_f32_e32 v0, v0
	v_sub_f32_e32 v128, 1.0, v156
	v_sub_f32_e32 v133, 1.0, v159
	v_sub_f32_e32 v132, 1.0, v158
	v_add_f32_e32 v0, 1.0, v0
	v_rcp_f32_e32 v123, v0
	v_mul_f32_e32 v0, 0xbfb8aa3b, v124
	v_exp_f32_e32 v0, v0
	v_pk_fma_f32 v[122:123], v[122:123], v[128:129], v[156:157]
	v_add_f32_e32 v0, 1.0, v0
	v_rcp_f32_e32 v124, v0
	v_mul_f32_e32 v0, 0xbfb8aa3b, v125
	v_exp_f32_e32 v0, v0
	s_nop 0
	v_add_f32_e32 v0, 1.0, v0
	v_rcp_f32_e32 v125, v0
	v_mul_f32_e32 v0, 0xbfb8aa3b, v118
	v_exp_f32_e32 v0, v0
	v_pk_fma_f32 v[124:125], v[124:125], v[132:133], v[158:159]
	global_store_dwordx4 v[126:127], v[122:125], off offset:64
	v_add_f32_e32 v0, 1.0, v0
	v_rcp_f32_e32 v118, v0
	v_mul_f32_e32 v0, 0xbfb8aa3b, v119
	v_exp_f32_e32 v0, v0
	s_waitcnt vmcnt(3)
	s_nop 1
	v_mov_b64_e32 v[122:123], v[232:233]
	v_mov_b64_e32 v[124:125], v[234:235]
	v_sub_f32_e32 v129, 1.0, v123
	v_add_f32_e32 v0, 1.0, v0
	v_rcp_f32_e32 v119, v0
	v_mul_f32_e32 v0, 0xbfb8aa3b, v120
	v_exp_f32_e32 v0, v0
	v_sub_f32_e32 v128, 1.0, v122
	v_sub_f32_e32 v133, 1.0, v125
	v_sub_f32_e32 v132, 1.0, v124
	v_add_f32_e32 v0, 1.0, v0
	v_rcp_f32_e32 v120, v0
	v_mul_f32_e32 v0, 0xbfb8aa3b, v121
	v_exp_f32_e32 v0, v0
	v_pk_fma_f32 v[118:119], v[118:119], v[128:129], v[122:123]
	v_add_f32_e32 v0, 1.0, v0
	v_rcp_f32_e32 v121, v0
	v_mul_f32_e32 v0, 0xbfb8aa3b, v114
	v_exp_f32_e32 v0, v0
	v_pk_fma_f32 v[120:121], v[120:121], v[132:133], v[124:125]
	global_store_dwordx4 v[126:127], v[118:121], off offset:128
	v_add_f32_e32 v0, 1.0, v0
	v_rcp_f32_e32 v114, v0
	v_mul_f32_e32 v0, 0xbfb8aa3b, v115
	v_exp_f32_e32 v0, v0
	s_waitcnt vmcnt(3)
	s_nop 1
	v_mov_b64_e32 v[118:119], v[236:237]
	v_mov_b64_e32 v[120:121], v[238:239]
	v_sub_f32_e32 v123, 1.0, v119
	v_add_f32_e32 v0, 1.0, v0
	v_rcp_f32_e32 v115, v0
	v_mul_f32_e32 v0, 0xbfb8aa3b, v116
	v_exp_f32_e32 v0, v0
	v_sub_f32_e32 v122, 1.0, v118
	v_sub_f32_e32 v125, 1.0, v121
	v_sub_f32_e32 v124, 1.0, v120
	v_add_f32_e32 v0, 1.0, v0
	v_rcp_f32_e32 v116, v0
	v_mul_f32_e32 v0, 0xbfb8aa3b, v117
	v_exp_f32_e32 v0, v0
	v_pk_fma_f32 v[114:115], v[114:115], v[122:123], v[118:119]
	v_add_f32_e32 v0, 1.0, v0
	v_rcp_f32_e32 v117, v0
	s_nop 0
	v_pk_fma_f32 v[116:117], v[116:117], v[124:125], v[120:121]
	global_store_dwordx4 v[126:127], v[114:117], off offset:192

.LBB0_1006:
	s_and_b64 vcc, exec, s[0:1]
	s_cbranch_vccz .LBB0_1016
	v_cmp_gt_i32_e32 vcc, s81, v118
	s_cbranch_vccz .Lrope_skip_1
	s_lshr_b32 s4, s28, 2
	s_and_b32 s4, s4, 0x7f0
	v_or_b32_e32 v119, s4, v167
	v_lshlrev_b32_e32 v119, 3, v119
	v_readlane_b32 s6, v254, 6
	v_readlane_b32 s7, v254, 7
	s_nop 4
	global_load_dwordx4 v[192:195], v119, s[6:7]
	global_load_dwordx4 v[196:199], v119, s[6:7] offset:64
	global_load_dwordx4 v[200:203], v[142:143], off
	global_load_dwordx4 v[204:207], v[142:143], off offset:64
.Lrope_skip_1:
	v_mul_f32_e32 v0, v111, v111
	v_fmac_f32_e32 v0, v110, v110
	v_fmac_f32_e32 v0, v112, v112
	v_fmac_f32_e32 v0, v113, v113
	v_fmac_f32_e32 v0, v106, v106
	v_fmac_f32_e32 v0, v107, v107
	v_fmac_f32_e32 v0, v108, v108
	v_fmac_f32_e32 v0, v109, v109
	v_fmac_f32_e32 v0, v102, v102
	v_fmac_f32_e32 v0, v103, v103
	v_pk_mul_f32 v[114:115], v[104:105], v[104:105]
	v_pk_mul_f32 v[116:117], v[98:99], v[98:99]
	v_add_f32_e32 v0, v114, v0
	v_add_f32_e32 v0, v115, v0
	v_add_f32_e32 v0, v116, v0
	v_pk_mul_f32 v[114:115], v[100:101], v[100:101]
	v_add_f32_e32 v0, v117, v0
	v_add_f32_e32 v0, v114, v0
	v_add_f32_e32 v0, v115, v0
	v_and_b32_e32 v115, 64, v214
	v_xor_b32_e32 v114, 16, v214
	v_add_u32_e32 v115, 64, v115
	v_cmp_lt_i32_e32 vcc, v114, v115
	s_and_b64 s[0:1], s[42:43], exec
	s_cselect_b32 s1, s18, s20
	v_cndmask_b32_e32 v114, v214, v114, vcc
	v_lshlrev_b32_e32 v114, 2, v114
	ds_bpermute_b32 v114, v114, v0
	s_cselect_b32 s0, s17, s19
	s_lshr_b32 s4, s28, 2
	s_and_b32 s4, s4, 0x7f0
	s_waitcnt lgkmcnt(0)
	v_add_f32_e32 v0, v0, v114
	v_xor_b32_e32 v114, 32, v214
	v_cmp_lt_i32_e32 vcc, v114, v115
	v_or_b32_e32 v115, s4, v167
	v_lshlrev_b32_e32 v119, 3, v115
	v_cndmask_b32_e32 v114, v214, v114, vcc
	v_lshlrev_b32_e32 v114, 2, v114
	ds_bpermute_b32 v114, v114, v0
	v_cmp_gt_i32_e32 vcc, s81, v118
	s_waitcnt lgkmcnt(0)
	v_add_f32_e32 v0, v0, v114
	v_fmamk_f32 v0, v0, 0x3c800000, v208
	v_rsq_f32_e32 v114, v0
	v_lshlrev_b32_e32 v0, 2, v138
	s_nop 1
	v_mov_b64_e32 v[120:121], v[224:225]
	v_mov_b64_e32 v[122:123], v[226:227]
	v_pk_mul_f32 v[116:117], v[110:111], v[114:115] op_sel_hi:[1,0]
	v_pk_mul_f32 v[116:117], v[120:121], v[116:117]
	v_pk_mul_f32 v[120:121], v[112:113], v[114:115] op_sel_hi:[1,0]
	s_nop 0
	v_pk_mul_f32 v[124:125], v[122:123], v[120:121]
	s_and_saveexec_b64 s[4:5], vcc
	s_cbranch_execz .LBB0_1009
	s_waitcnt vmcnt(3)
	v_mov_b64_e32 v[120:121], v[192:193]
	v_mov_b64_e32 v[122:123], v[194:195]
	v_pk_mul_f32 v[128:129], v[116:117], v[120:121] op_sel:[1,1] op_sel_hi:[1,0]
	v_pk_mul_f32 v[126:127], v[116:117], v[120:121]
	v_pk_fma_f32 v[116:117], v[116:117], v[120:121], v[128:129] op_sel_hi:[0,1,1]
	v_mul_f32_e32 v116, v125, v123
	v_pk_fma_f32 v[120:121], v[124:125], v[122:123], v[116:117] op_sel_hi:[1,1,0] neg_lo:[0,0,1] neg_hi:[0,0,1]
	v_mul_f32_e32 v116, v125, v122
	v_pk_fma_f32 v[122:123], v[124:125], v[122:123], v[116:117] op_sel:[0,1,0] op_sel_hi:[1,0,0]
	v_sub_f32_e32 v116, v126, v128
	v_mov_b32_e32 v124, v120
	v_mov_b32_e32 v125, v122
.LBB0_1009:
	s_or_b64 exec, exec, s[4:5]
	v_lshl_add_u64 v[120:121], s[0:1], 0, v[0:1]
	v_readlane_b32 s0, v254, 35
	v_readlane_b32 s1, v254, 36
	v_pk_mul_f32 v[128:129], v[154:155], v[116:117]
	v_lshlrev_b32_e32 v0, 1, v138
	v_mov_b64_e32 v[122:123], s[0:1]
	v_mad_i64_i32 v[122:123], s[0:1], v118, s52, v[122:123]
	s_lshl_b32 s0, s27, 1
	s_mov_b32 s1, s35
	v_lshl_add_u64 v[122:123], v[122:123], 0, s[0:1]
	v_lshl_add_u64 v[126:127], s[76:77], 1, v[122:123]
	v_mov_b32_e32 v122, v154
	v_mov_b32_e32 v123, v154
	v_pk_mul_f32 v[124:125], v[122:123], v[124:125]
	v_lshl_add_u64 v[116:117], v[126:127], 0, v[0:1]
	v_cvt_pk_bf16_f32 v240, v128, v129
	v_cvt_pk_bf16_f32 v241, v124, v125
	s_nop 1
	v_mov_b64_e32 v[124:125], v[228:229]
	v_mov_b64_e32 v[126:127], v[230:231]
	v_mov_b32_e32 v115, v114
	v_pk_mul_f32 v[128:129], v[106:107], v[114:115]
	v_pk_mul_f32 v[124:125], v[128:129], v[124:125]
	v_pk_mul_f32 v[128:129], v[108:109], v[114:115]
	s_nop 0
	v_pk_mul_f32 v[126:127], v[128:129], v[126:127]
	s_and_saveexec_b64 s[0:1], vcc
	s_cbranch_execz .LBB0_1011
	s_waitcnt vmcnt(2)
	v_mov_b64_e32 v[128:129], v[196:197]
	v_mov_b64_e32 v[130:131], v[198:199]
	v_pk_mul_f32 v[156:157], v[124:125], v[128:129] op_sel:[1,1] op_sel_hi:[1,0]
	v_mul_f32_e32 v0, v127, v131
	v_pk_mul_f32 v[132:133], v[124:125], v[128:129]
	v_pk_fma_f32 v[124:125], v[124:125], v[128:129], v[156:157] op_sel_hi:[0,1,1]
	v_pk_fma_f32 v[128:129], v[126:127], v[130:131], v[0:1] op_sel_hi:[1,1,0] neg_lo:[0,0,1] neg_hi:[0,0,1]
	v_mul_f32_e32 v0, v127, v130
	v_pk_fma_f32 v[130:131], v[126:127], v[130:131], v[0:1] op_sel:[0,1,0] op_sel_hi:[1,0,0]
	v_sub_f32_e32 v124, v132, v156
	v_mov_b32_e32 v126, v128
	v_mov_b32_e32 v127, v130
.LBB0_1011:
	s_or_b64 exec, exec, s[0:1]
	v_pk_mul_f32 v[122:123], v[122:123], v[126:127]
	v_pk_mul_f32 v[124:125], v[154:155], v[124:125]
	v_pk_mul_f32 v[126:127], v[102:103], v[114:115]
	v_cvt_pk_bf16_f32 v242, v124, v125
	v_cvt_pk_bf16_f32 v243, v122, v123
	s_nop 1
	v_mov_b64_e32 v[122:123], v[232:233]
	v_mov_b64_e32 v[124:125], v[234:235]
	v_pk_mul_f32 v[122:123], v[126:127], v[122:123]
	v_pk_mul_f32 v[126:127], v[104:105], v[114:115]
	s_nop 0
	v_pk_mul_f32 v[126:127], v[126:127], v[124:125]
	s_and_saveexec_b64 s[0:1], vcc
	s_cbranch_execz .LBB0_1013
	s_waitcnt vmcnt(1)
	v_mov_b64_e32 v[128:129], v[200:201]
	v_mov_b64_e32 v[130:131], v[202:203]
	v_pk_mul_f32 v[132:133], v[122:123], v[128:129] op_sel:[1,1] op_sel_hi:[1,0]
	v_mul_f32_e32 v0, v127, v131
	v_pk_mul_f32 v[124:125], v[122:123], v[128:129]
	v_pk_fma_f32 v[122:123], v[122:123], v[128:129], v[132:133] op_sel_hi:[0,1,1]
	v_pk_fma_f32 v[128:129], v[126:127], v[130:131], v[0:1] op_sel_hi:[1,1,0] neg_lo:[0,0,1] neg_hi:[0,0,1]
	v_mul_f32_e32 v0, v127, v130
	v_pk_fma_f32 v[130:131], v[126:127], v[130:131], v[0:1] op_sel:[0,1,0] op_sel_hi:[1,0,0]
	v_sub_f32_e32 v122, v124, v132
	v_mov_b32_e32 v126, v128
	v_mov_b32_e32 v127, v130
.LBB0_1013:
	s_or_b64 exec, exec, s[0:1]
	v_mov_b32_e32 v124, v154
	v_mov_b32_e32 v125, v154
	v_pk_mul_f32 v[126:127], v[124:125], v[126:127]
	v_pk_mul_f32 v[122:123], v[154:155], v[122:123]
	v_pk_mul_f32 v[128:129], v[100:101], v[114:115]
	v_cvt_pk_bf16_f32 v244, v122, v123
	v_cvt_pk_bf16_f32 v245, v126, v127
	s_nop 1
	v_mov_b64_e32 v[120:121], v[236:237]
	v_mov_b64_e32 v[122:123], v[238:239]
	v_pk_mul_f32 v[126:127], v[98:99], v[114:115]
	v_pk_mul_f32 v[114:115], v[126:127], v[120:121]
	v_pk_mul_f32 v[120:121], v[128:129], v[122:123]
	s_and_saveexec_b64 s[0:1], vcc
	s_cbranch_execz .LBB0_1015
	s_waitcnt vmcnt(0)
	v_mov_b64_e32 v[126:127], v[204:205]
	v_mov_b64_e32 v[128:129], v[206:207]
	v_pk_mul_f32 v[130:131], v[114:115], v[126:127] op_sel:[1,1] op_sel_hi:[1,0]
	v_mul_f32_e32 v0, v121, v129
	v_pk_mul_f32 v[122:123], v[114:115], v[126:127]
	v_pk_fma_f32 v[114:115], v[114:115], v[126:127], v[130:131] op_sel_hi:[0,1,1]
	v_pk_fma_f32 v[126:127], v[120:121], v[128:129], v[0:1] op_sel_hi:[1,1,0] neg_lo:[0,0,1] neg_hi:[0,0,1]
	v_mul_f32_e32 v0, v121, v128
	v_pk_fma_f32 v[128:129], v[120:121], v[128:129], v[0:1] op_sel:[0,1,0] op_sel_hi:[1,0,0]
	v_sub_f32_e32 v114, v122, v130
	v_mov_b32_e32 v120, v126
	v_mov_b32_e32 v121, v128

.LBB0_1054:
	s_and_b64 vcc, exec, s[0:1]
	s_cbranch_vccz .LBB0_1064
	v_cmp_gt_i32_e32 vcc, s81, v102
	s_cbranch_vccz .Lrope_skip_2
	s_lshr_b32 s4, s28, 2
	s_and_b32 s4, s4, 0x7f0
	v_or_b32_e32 v103, s4, v167
	v_lshlrev_b32_e32 v103, 3, v103
	v_readlane_b32 s6, v254, 6
	v_readlane_b32 s7, v254, 7
	s_nop 4
	global_load_dwordx4 v[192:195], v103, s[6:7]
	global_load_dwordx4 v[196:199], v103, s[6:7] offset:64
	global_load_dwordx4 v[200:203], v[144:145], off
	global_load_dwordx4 v[204:207], v[144:145], off offset:64
.Lrope_skip_2:
	v_mul_f32_e32 v0, v95, v95
	v_fmac_f32_e32 v0, v94, v94
	v_fmac_f32_e32 v0, v96, v96
	v_fmac_f32_e32 v0, v97, v97
	v_fmac_f32_e32 v0, v90, v90
	v_fmac_f32_e32 v0, v91, v91
	v_fmac_f32_e32 v0, v92, v92
	v_fmac_f32_e32 v0, v93, v93
	v_fmac_f32_e32 v0, v86, v86
	v_fmac_f32_e32 v0, v87, v87
	v_pk_mul_f32 v[98:99], v[88:89], v[88:89]
	v_pk_mul_f32 v[100:101], v[82:83], v[82:83]
	v_add_f32_e32 v0, v98, v0
	v_add_f32_e32 v0, v99, v0
	v_add_f32_e32 v0, v100, v0
	v_pk_mul_f32 v[98:99], v[84:85], v[84:85]
	v_add_f32_e32 v0, v101, v0
	v_add_f32_e32 v0, v98, v0
	v_add_f32_e32 v0, v99, v0
	v_and_b32_e32 v99, 64, v214
	v_xor_b32_e32 v98, 16, v214
	v_add_u32_e32 v99, 64, v99
	v_cmp_lt_i32_e32 vcc, v98, v99
	s_and_b64 s[0:1], s[42:43], exec
	s_cselect_b32 s1, s18, s20
	v_cndmask_b32_e32 v98, v214, v98, vcc
	v_lshlrev_b32_e32 v98, 2, v98
	ds_bpermute_b32 v98, v98, v0
	s_cselect_b32 s0, s17, s19
	s_lshr_b32 s4, s28, 2
	s_and_b32 s4, s4, 0x7f0
	s_waitcnt lgkmcnt(0)
	v_add_f32_e32 v0, v0, v98
	v_xor_b32_e32 v98, 32, v214
	v_cmp_lt_i32_e32 vcc, v98, v99
	v_or_b32_e32 v99, s4, v167
	v_lshlrev_b32_e32 v103, 3, v99
	v_cndmask_b32_e32 v98, v214, v98, vcc
	v_lshlrev_b32_e32 v98, 2, v98
	ds_bpermute_b32 v98, v98, v0
	v_cmp_gt_i32_e32 vcc, s81, v102
	s_waitcnt lgkmcnt(0)
	v_add_f32_e32 v0, v0, v98
	v_fmamk_f32 v0, v0, 0x3c800000, v208
	v_rsq_f32_e32 v98, v0
	v_lshlrev_b32_e32 v0, 2, v138
	s_nop 1
	v_mov_b64_e32 v[104:105], v[224:225]
	v_mov_b64_e32 v[106:107], v[226:227]
	v_pk_mul_f32 v[100:101], v[94:95], v[98:99] op_sel_hi:[1,0]
	v_pk_mul_f32 v[100:101], v[104:105], v[100:101]
	v_pk_mul_f32 v[104:105], v[96:97], v[98:99] op_sel_hi:[1,0]
	s_nop 0
	v_pk_mul_f32 v[108:109], v[106:107], v[104:105]
	s_and_saveexec_b64 s[4:5], vcc
	s_cbranch_execz .LBB0_1057
	s_waitcnt vmcnt(3)
	v_mov_b64_e32 v[104:105], v[192:193]
	v_mov_b64_e32 v[106:107], v[194:195]
	v_pk_mul_f32 v[112:113], v[100:101], v[104:105] op_sel:[1,1] op_sel_hi:[1,0]
	v_pk_mul_f32 v[110:111], v[100:101], v[104:105]
	v_pk_fma_f32 v[100:101], v[100:101], v[104:105], v[112:113] op_sel_hi:[0,1,1]
	v_mul_f32_e32 v100, v109, v107
	v_pk_fma_f32 v[104:105], v[108:109], v[106:107], v[100:101] op_sel_hi:[1,1,0] neg_lo:[0,0,1] neg_hi:[0,0,1]
	v_mul_f32_e32 v100, v109, v106
	v_pk_fma_f32 v[106:107], v[108:109], v[106:107], v[100:101] op_sel:[0,1,0] op_sel_hi:[1,0,0]
	v_sub_f32_e32 v100, v110, v112
	v_mov_b32_e32 v108, v104
	v_mov_b32_e32 v109, v106
.LBB0_1057:
	s_or_b64 exec, exec, s[4:5]
	v_lshl_add_u64 v[104:105], s[0:1], 0, v[0:1]
	v_readlane_b32 s0, v254, 35
	v_readlane_b32 s1, v254, 36
	v_pk_mul_f32 v[112:113], v[154:155], v[100:101]
	v_lshlrev_b32_e32 v0, 1, v138
	v_mov_b64_e32 v[106:107], s[0:1]
	v_mad_i64_i32 v[106:107], s[0:1], v102, s52, v[106:107]
	s_lshl_b32 s0, s27, 1
	s_mov_b32 s1, s35
	v_lshl_add_u64 v[106:107], v[106:107], 0, s[0:1]
	v_lshl_add_u64 v[110:111], s[76:77], 1, v[106:107]
	v_mov_b32_e32 v106, v154
	v_mov_b32_e32 v107, v154
	v_pk_mul_f32 v[108:109], v[106:107], v[108:109]
	v_lshl_add_u64 v[100:101], v[110:111], 0, v[0:1]
	v_cvt_pk_bf16_f32 v240, v112, v113
	v_cvt_pk_bf16_f32 v241, v108, v109
	s_nop 1
	v_mov_b64_e32 v[108:109], v[228:229]
	v_mov_b64_e32 v[110:111], v[230:231]
	v_mov_b32_e32 v99, v98
	v_pk_mul_f32 v[112:113], v[90:91], v[98:99]
	v_pk_mul_f32 v[108:109], v[112:113], v[108:109]
	v_pk_mul_f32 v[112:113], v[92:93], v[98:99]
	s_nop 0
	v_pk_mul_f32 v[110:111], v[112:113], v[110:111]
	s_and_saveexec_b64 s[0:1], vcc
	s_cbranch_execz .LBB0_1059
	s_waitcnt vmcnt(2)
	v_mov_b64_e32 v[112:113], v[196:197]
	v_mov_b64_e32 v[114:115], v[198:199]
	v_pk_mul_f32 v[118:119], v[108:109], v[112:113] op_sel:[1,1] op_sel_hi:[1,0]
	v_mul_f32_e32 v0, v111, v115
	v_pk_mul_f32 v[116:117], v[108:109], v[112:113]
	v_pk_fma_f32 v[108:109], v[108:109], v[112:113], v[118:119] op_sel_hi:[0,1,1]
	v_pk_fma_f32 v[112:113], v[110:111], v[114:115], v[0:1] op_sel_hi:[1,1,0] neg_lo:[0,0,1] neg_hi:[0,0,1]
	v_mul_f32_e32 v0, v111, v114
	v_pk_fma_f32 v[114:115], v[110:111], v[114:115], v[0:1] op_sel:[0,1,0] op_sel_hi:[1,0,0]
	v_sub_f32_e32 v108, v116, v118
	v_mov_b32_e32 v110, v112
	v_mov_b32_e32 v111, v114
.LBB0_1059:
	s_or_b64 exec, exec, s[0:1]
	v_pk_mul_f32 v[106:107], v[106:107], v[110:111]
	v_pk_mul_f32 v[108:109], v[154:155], v[108:109]
	v_pk_mul_f32 v[110:111], v[86:87], v[98:99]
	v_cvt_pk_bf16_f32 v242, v108, v109
	v_cvt_pk_bf16_f32 v243, v106, v107
	s_nop 1
	v_mov_b64_e32 v[106:107], v[232:233]
	v_mov_b64_e32 v[108:109], v[234:235]
	v_pk_mul_f32 v[106:107], v[110:111], v[106:107]
	v_pk_mul_f32 v[110:111], v[88:89], v[98:99]
	s_nop 0
	v_pk_mul_f32 v[110:111], v[110:111], v[108:109]
	s_and_saveexec_b64 s[0:1], vcc
	s_cbranch_execz .LBB0_1061
	s_waitcnt vmcnt(1)
	v_mov_b64_e32 v[112:113], v[200:201]
	v_mov_b64_e32 v[114:115], v[202:203]
	v_pk_mul_f32 v[116:117], v[106:107], v[112:113] op_sel:[1,1] op_sel_hi:[1,0]
	v_mul_f32_e32 v0, v111, v115
	v_pk_mul_f32 v[108:109], v[106:107], v[112:113]
	v_pk_fma_f32 v[106:107], v[106:107], v[112:113], v[116:117] op_sel_hi:[0,1,1]
	v_pk_fma_f32 v[112:113], v[110:111], v[114:115], v[0:1] op_sel_hi:[1,1,0] neg_lo:[0,0,1] neg_hi:[0,0,1]
	v_mul_f32_e32 v0, v111, v114
	v_pk_fma_f32 v[114:115], v[110:111], v[114:115], v[0:1] op_sel:[0,1,0] op_sel_hi:[1,0,0]
	v_sub_f32_e32 v106, v108, v116
	v_mov_b32_e32 v110, v112
	v_mov_b32_e32 v111, v114
.LBB0_1061:
	s_or_b64 exec, exec, s[0:1]
	v_mov_b32_e32 v108, v154
	v_mov_b32_e32 v109, v154
	v_pk_mul_f32 v[110:111], v[108:109], v[110:111]
	v_pk_mul_f32 v[106:107], v[154:155], v[106:107]
	v_pk_mul_f32 v[112:113], v[84:85], v[98:99]
	v_cvt_pk_bf16_f32 v244, v106, v107
	v_cvt_pk_bf16_f32 v245, v110, v111
	s_nop 1
	v_mov_b64_e32 v[104:105], v[236:237]
	v_mov_b64_e32 v[106:107], v[238:239]
	v_pk_mul_f32 v[110:111], v[82:83], v[98:99]
	v_pk_mul_f32 v[98:99], v[110:111], v[104:105]
	v_pk_mul_f32 v[104:105], v[112:113], v[106:107]
	s_and_saveexec_b64 s[0:1], vcc
	s_cbranch_execz .LBB0_1063
	s_waitcnt vmcnt(0)
	v_mov_b64_e32 v[110:111], v[204:205]
	v_mov_b64_e32 v[112:113], v[206:207]
	v_pk_mul_f32 v[114:115], v[98:99], v[110:111] op_sel:[1,1] op_sel_hi:[1,0]
	v_mul_f32_e32 v0, v105, v113
	v_pk_mul_f32 v[106:107], v[98:99], v[110:111]
	v_pk_fma_f32 v[98:99], v[98:99], v[110:111], v[114:115] op_sel_hi:[0,1,1]
	v_pk_fma_f32 v[110:111], v[104:105], v[112:113], v[0:1] op_sel_hi:[1,1,0] neg_lo:[0,0,1] neg_hi:[0,0,1]
	v_mul_f32_e32 v0, v105, v112
	v_pk_fma_f32 v[112:113], v[104:105], v[112:113], v[0:1] op_sel:[0,1,0] op_sel_hi:[1,0,0]
	v_sub_f32_e32 v98, v106, v114
	v_mov_b32_e32 v104, v110
	v_mov_b32_e32 v105, v112

.LBB0_1102:
	s_and_b64 vcc, exec, s[0:1]
	s_cbranch_vccz .LBB0_1112
	v_cmp_gt_i32_e32 vcc, s81, v86
	s_cbranch_vccz .Lrope_skip_3
	s_lshr_b32 s4, s28, 2
	s_and_b32 s4, s4, 0x7f0
	v_or_b32_e32 v87, s4, v167
	v_lshlrev_b32_e32 v87, 3, v87
	v_readlane_b32 s6, v254, 6
	v_readlane_b32 s7, v254, 7
	s_nop 4
	global_load_dwordx4 v[192:195], v87, s[6:7]
	global_load_dwordx4 v[196:199], v87, s[6:7] offset:64
	global_load_dwordx4 v[200:203], v[146:147], off
	global_load_dwordx4 v[204:207], v[146:147], off offset:64
.Lrope_skip_3:
	v_mul_f32_e32 v0, v79, v79
	v_fmac_f32_e32 v0, v78, v78
	v_fmac_f32_e32 v0, v80, v80
	v_fmac_f32_e32 v0, v81, v81
	v_fmac_f32_e32 v0, v74, v74
	v_fmac_f32_e32 v0, v75, v75
	v_fmac_f32_e32 v0, v76, v76
	v_fmac_f32_e32 v0, v77, v77
	v_fmac_f32_e32 v0, v70, v70
	v_fmac_f32_e32 v0, v71, v71
	v_pk_mul_f32 v[82:83], v[72:73], v[72:73]
	v_pk_mul_f32 v[84:85], v[66:67], v[66:67]
	v_add_f32_e32 v0, v82, v0
	v_add_f32_e32 v0, v83, v0
	v_add_f32_e32 v0, v84, v0
	v_pk_mul_f32 v[82:83], v[68:69], v[68:69]
	v_add_f32_e32 v0, v85, v0
	v_add_f32_e32 v0, v82, v0
	v_add_f32_e32 v0, v83, v0
	v_and_b32_e32 v83, 64, v214
	v_xor_b32_e32 v82, 16, v214
	v_add_u32_e32 v83, 64, v83
	v_cmp_lt_i32_e32 vcc, v82, v83
	s_and_b64 s[0:1], s[42:43], exec
	s_cselect_b32 s1, s18, s20
	v_cndmask_b32_e32 v82, v214, v82, vcc
	v_lshlrev_b32_e32 v82, 2, v82
	ds_bpermute_b32 v82, v82, v0
	s_cselect_b32 s0, s17, s19
	s_lshr_b32 s4, s28, 2
	s_and_b32 s4, s4, 0x7f0
	s_waitcnt lgkmcnt(0)
	v_add_f32_e32 v0, v0, v82
	v_xor_b32_e32 v82, 32, v214
	v_cmp_lt_i32_e32 vcc, v82, v83
	v_or_b32_e32 v83, s4, v167
	v_lshlrev_b32_e32 v87, 3, v83
	v_cndmask_b32_e32 v82, v214, v82, vcc
	v_lshlrev_b32_e32 v82, 2, v82
	ds_bpermute_b32 v82, v82, v0
	v_cmp_gt_i32_e32 vcc, s81, v86
	s_waitcnt lgkmcnt(0)
	v_add_f32_e32 v0, v0, v82
	v_fmamk_f32 v0, v0, 0x3c800000, v208
	v_rsq_f32_e32 v82, v0
	v_lshlrev_b32_e32 v0, 2, v138
	s_nop 1
	v_mov_b64_e32 v[88:89], v[224:225]
	v_mov_b64_e32 v[90:91], v[226:227]
	v_pk_mul_f32 v[84:85], v[78:79], v[82:83] op_sel_hi:[1,0]
	v_pk_mul_f32 v[84:85], v[88:89], v[84:85]
	v_pk_mul_f32 v[88:89], v[80:81], v[82:83] op_sel_hi:[1,0]
	s_nop 0
	v_pk_mul_f32 v[92:93], v[90:91], v[88:89]
	s_and_saveexec_b64 s[4:5], vcc
	s_cbranch_execz .LBB0_1105
	s_waitcnt vmcnt(3)
	v_mov_b64_e32 v[88:89], v[192:193]
	v_mov_b64_e32 v[90:91], v[194:195]
	v_pk_mul_f32 v[96:97], v[84:85], v[88:89] op_sel:[1,1] op_sel_hi:[1,0]
	v_pk_mul_f32 v[94:95], v[84:85], v[88:89]
	v_pk_fma_f32 v[84:85], v[84:85], v[88:89], v[96:97] op_sel_hi:[0,1,1]
	v_mul_f32_e32 v84, v93, v91
	v_pk_fma_f32 v[88:89], v[92:93], v[90:91], v[84:85] op_sel_hi:[1,1,0] neg_lo:[0,0,1] neg_hi:[0,0,1]
	v_mul_f32_e32 v84, v93, v90
	v_pk_fma_f32 v[90:91], v[92:93], v[90:91], v[84:85] op_sel:[0,1,0] op_sel_hi:[1,0,0]
	v_sub_f32_e32 v84, v94, v96
	v_mov_b32_e32 v92, v88
	v_mov_b32_e32 v93, v90
.LBB0_1105:
	s_or_b64 exec, exec, s[4:5]
	v_lshl_add_u64 v[88:89], s[0:1], 0, v[0:1]
	v_readlane_b32 s0, v254, 35
	v_readlane_b32 s1, v254, 36
	v_pk_mul_f32 v[96:97], v[154:155], v[84:85]
	v_lshlrev_b32_e32 v0, 1, v138
	v_mov_b64_e32 v[90:91], s[0:1]
	v_mad_i64_i32 v[90:91], s[0:1], v86, s52, v[90:91]
	s_lshl_b32 s0, s27, 1
	s_mov_b32 s1, s35
	v_lshl_add_u64 v[90:91], v[90:91], 0, s[0:1]
	v_lshl_add_u64 v[94:95], s[76:77], 1, v[90:91]
	v_mov_b32_e32 v90, v154
	v_mov_b32_e32 v91, v154
	v_pk_mul_f32 v[92:93], v[90:91], v[92:93]
	v_lshl_add_u64 v[84:85], v[94:95], 0, v[0:1]
	v_cvt_pk_bf16_f32 v240, v96, v97
	v_cvt_pk_bf16_f32 v241, v92, v93
	s_nop 1
	v_mov_b64_e32 v[92:93], v[228:229]
	v_mov_b64_e32 v[94:95], v[230:231]
	v_mov_b32_e32 v83, v82
	v_pk_mul_f32 v[96:97], v[74:75], v[82:83]
	v_pk_mul_f32 v[92:93], v[96:97], v[92:93]
	v_pk_mul_f32 v[96:97], v[76:77], v[82:83]
	s_nop 0
	v_pk_mul_f32 v[94:95], v[96:97], v[94:95]
	s_and_saveexec_b64 s[0:1], vcc
	s_cbranch_execz .LBB0_1107
	s_waitcnt vmcnt(2)
	v_mov_b64_e32 v[96:97], v[196:197]
	v_mov_b64_e32 v[98:99], v[198:199]
	v_pk_mul_f32 v[102:103], v[92:93], v[96:97] op_sel:[1,1] op_sel_hi:[1,0]
	v_mul_f32_e32 v0, v95, v99
	v_pk_mul_f32 v[100:101], v[92:93], v[96:97]
	v_pk_fma_f32 v[92:93], v[92:93], v[96:97], v[102:103] op_sel_hi:[0,1,1]
	v_pk_fma_f32 v[96:97], v[94:95], v[98:99], v[0:1] op_sel_hi:[1,1,0] neg_lo:[0,0,1] neg_hi:[0,0,1]
	v_mul_f32_e32 v0, v95, v98
	v_pk_fma_f32 v[98:99], v[94:95], v[98:99], v[0:1] op_sel:[0,1,0] op_sel_hi:[1,0,0]
	v_sub_f32_e32 v92, v100, v102
	v_mov_b32_e32 v94, v96
	v_mov_b32_e32 v95, v98
.LBB0_1107:
	s_or_b64 exec, exec, s[0:1]
	v_pk_mul_f32 v[90:91], v[90:91], v[94:95]
	v_pk_mul_f32 v[92:93], v[154:155], v[92:93]
	v_pk_mul_f32 v[94:95], v[70:71], v[82:83]
	v_cvt_pk_bf16_f32 v242, v92, v93
	v_cvt_pk_bf16_f32 v243, v90, v91
	s_nop 1
	v_mov_b64_e32 v[90:91], v[232:233]
	v_mov_b64_e32 v[92:93], v[234:235]
	v_pk_mul_f32 v[90:91], v[94:95], v[90:91]
	v_pk_mul_f32 v[94:95], v[72:73], v[82:83]
	s_nop 0
	v_pk_mul_f32 v[94:95], v[94:95], v[92:93]
	s_and_saveexec_b64 s[0:1], vcc
	s_cbranch_execz .LBB0_1109
	s_waitcnt vmcnt(1)
	v_mov_b64_e32 v[96:97], v[200:201]
	v_mov_b64_e32 v[98:99], v[202:203]
	v_pk_mul_f32 v[100:101], v[90:91], v[96:97] op_sel:[1,1] op_sel_hi:[1,0]
	v_mul_f32_e32 v0, v95, v99
	v_pk_mul_f32 v[92:93], v[90:91], v[96:97]
	v_pk_fma_f32 v[90:91], v[90:91], v[96:97], v[100:101] op_sel_hi:[0,1,1]
	v_pk_fma_f32 v[96:97], v[94:95], v[98:99], v[0:1] op_sel_hi:[1,1,0] neg_lo:[0,0,1] neg_hi:[0,0,1]
	v_mul_f32_e32 v0, v95, v98
	v_pk_fma_f32 v[98:99], v[94:95], v[98:99], v[0:1] op_sel:[0,1,0] op_sel_hi:[1,0,0]
	v_sub_f32_e32 v90, v92, v100
	v_mov_b32_e32 v94, v96
	v_mov_b32_e32 v95, v98
.LBB0_1109:
	s_or_b64 exec, exec, s[0:1]
	v_mov_b32_e32 v92, v154
	v_mov_b32_e32 v93, v154
	v_pk_mul_f32 v[94:95], v[92:93], v[94:95]
	v_pk_mul_f32 v[90:91], v[154:155], v[90:91]
	v_pk_mul_f32 v[96:97], v[68:69], v[82:83]
	v_cvt_pk_bf16_f32 v244, v90, v91
	v_cvt_pk_bf16_f32 v245, v94, v95
	s_nop 1
	v_mov_b64_e32 v[88:89], v[236:237]
	v_mov_b64_e32 v[90:91], v[238:239]
	v_pk_mul_f32 v[94:95], v[66:67], v[82:83]
	v_pk_mul_f32 v[82:83], v[94:95], v[88:89]
	v_pk_mul_f32 v[88:89], v[96:97], v[90:91]
	s_and_saveexec_b64 s[0:1], vcc
	s_cbranch_execz .LBB0_1111
	s_waitcnt vmcnt(0)
	v_mov_b64_e32 v[94:95], v[204:205]
	v_mov_b64_e32 v[96:97], v[206:207]
	v_pk_mul_f32 v[98:99], v[82:83], v[94:95] op_sel:[1,1] op_sel_hi:[1,0]
	v_mul_f32_e32 v0, v89, v97
	v_pk_mul_f32 v[90:91], v[82:83], v[94:95]
	v_pk_fma_f32 v[82:83], v[82:83], v[94:95], v[98:99] op_sel_hi:[0,1,1]
	v_pk_fma_f32 v[94:95], v[88:89], v[96:97], v[0:1] op_sel_hi:[1,1,0] neg_lo:[0,0,1] neg_hi:[0,0,1]
	v_mul_f32_e32 v0, v89, v96
	v_pk_fma_f32 v[96:97], v[88:89], v[96:97], v[0:1] op_sel:[0,1,0] op_sel_hi:[1,0,0]
	v_sub_f32_e32 v82, v90, v98
	v_mov_b32_e32 v88, v94
	v_mov_b32_e32 v89, v96

.LBB0_1150:
	s_and_b64 vcc, exec, s[0:1]
	s_cbranch_vccz .LBB0_1160
	v_cmp_gt_i32_e32 vcc, s81, v70
	s_cbranch_vccz .Lrope_skip_4
	s_lshr_b32 s4, s28, 2
	s_and_b32 s4, s4, 0x7f0
	v_or_b32_e32 v71, s4, v167
	v_lshlrev_b32_e32 v71, 3, v71
	v_readlane_b32 s6, v254, 6
	v_readlane_b32 s7, v254, 7
	s_nop 4
	global_load_dwordx4 v[192:195], v71, s[6:7]
	global_load_dwordx4 v[196:199], v71, s[6:7] offset:64
	global_load_dwordx4 v[200:203], v[140:141], off
	global_load_dwordx4 v[204:207], v[140:141], off offset:64
.Lrope_skip_4:
	v_mul_f32_e32 v0, v63, v63
	v_fmac_f32_e32 v0, v62, v62
	v_fmac_f32_e32 v0, v64, v64
	v_fmac_f32_e32 v0, v65, v65
	v_fmac_f32_e32 v0, v58, v58
	v_fmac_f32_e32 v0, v59, v59
	v_fmac_f32_e32 v0, v60, v60
	v_fmac_f32_e32 v0, v61, v61
	v_fmac_f32_e32 v0, v54, v54
	v_fmac_f32_e32 v0, v55, v55
	v_pk_mul_f32 v[66:67], v[56:57], v[56:57]
	v_pk_mul_f32 v[68:69], v[50:51], v[50:51]
	v_add_f32_e32 v0, v66, v0
	v_add_f32_e32 v0, v67, v0
	v_add_f32_e32 v0, v68, v0
	v_pk_mul_f32 v[66:67], v[52:53], v[52:53]
	v_add_f32_e32 v0, v69, v0
	v_add_f32_e32 v0, v66, v0
	v_add_f32_e32 v0, v67, v0
	v_and_b32_e32 v67, 64, v214
	v_xor_b32_e32 v66, 16, v214
	v_add_u32_e32 v67, 64, v67
	v_cmp_lt_i32_e32 vcc, v66, v67
	s_and_b64 s[0:1], s[42:43], exec
	s_cselect_b32 s1, s18, s20
	v_cndmask_b32_e32 v66, v214, v66, vcc
	v_lshlrev_b32_e32 v66, 2, v66
	ds_bpermute_b32 v66, v66, v0
	s_cselect_b32 s0, s17, s19
	s_lshr_b32 s4, s28, 2
	s_and_b32 s4, s4, 0x7f0
	s_waitcnt lgkmcnt(0)
	v_add_f32_e32 v0, v0, v66
	v_xor_b32_e32 v66, 32, v214
	v_cmp_lt_i32_e32 vcc, v66, v67
	v_or_b32_e32 v67, s4, v167
	v_lshlrev_b32_e32 v71, 3, v67
	v_cndmask_b32_e32 v66, v214, v66, vcc
	v_lshlrev_b32_e32 v66, 2, v66
	ds_bpermute_b32 v66, v66, v0
	v_cmp_gt_i32_e32 vcc, s81, v70
	s_waitcnt lgkmcnt(0)
	v_add_f32_e32 v0, v0, v66
	v_fmamk_f32 v0, v0, 0x3c800000, v208
	v_rsq_f32_e32 v66, v0
	v_lshlrev_b32_e32 v0, 2, v138
	s_nop 1
	v_mov_b64_e32 v[72:73], v[224:225]
	v_mov_b64_e32 v[74:75], v[226:227]
	v_pk_mul_f32 v[68:69], v[62:63], v[66:67] op_sel_hi:[1,0]
	v_pk_mul_f32 v[68:69], v[72:73], v[68:69]
	v_pk_mul_f32 v[72:73], v[64:65], v[66:67] op_sel_hi:[1,0]
	s_nop 0
	v_pk_mul_f32 v[76:77], v[74:75], v[72:73]
	s_and_saveexec_b64 s[4:5], vcc
	s_cbranch_execz .LBB0_1153
	s_waitcnt vmcnt(3)
	v_mov_b64_e32 v[72:73], v[192:193]
	v_mov_b64_e32 v[74:75], v[194:195]
	v_pk_mul_f32 v[80:81], v[68:69], v[72:73] op_sel:[1,1] op_sel_hi:[1,0]
	v_pk_mul_f32 v[78:79], v[68:69], v[72:73]
	v_pk_fma_f32 v[68:69], v[68:69], v[72:73], v[80:81] op_sel_hi:[0,1,1]
	v_mul_f32_e32 v68, v77, v75
	v_pk_fma_f32 v[72:73], v[76:77], v[74:75], v[68:69] op_sel_hi:[1,1,0] neg_lo:[0,0,1] neg_hi:[0,0,1]
	v_mul_f32_e32 v68, v77, v74
	v_pk_fma_f32 v[74:75], v[76:77], v[74:75], v[68:69] op_sel:[0,1,0] op_sel_hi:[1,0,0]
	v_sub_f32_e32 v68, v78, v80
	v_mov_b32_e32 v76, v72
	v_mov_b32_e32 v77, v74
.LBB0_1153:
	s_or_b64 exec, exec, s[4:5]
	v_lshl_add_u64 v[72:73], s[0:1], 0, v[0:1]
	v_readlane_b32 s0, v254, 35
	v_readlane_b32 s1, v254, 36
	v_pk_mul_f32 v[80:81], v[154:155], v[68:69]
	v_lshlrev_b32_e32 v0, 1, v138
	v_mov_b64_e32 v[74:75], s[0:1]
	v_mad_i64_i32 v[74:75], s[0:1], v70, s52, v[74:75]
	s_lshl_b32 s0, s27, 1
	s_mov_b32 s1, s35
	v_lshl_add_u64 v[74:75], v[74:75], 0, s[0:1]
	v_lshl_add_u64 v[78:79], s[76:77], 1, v[74:75]
	v_mov_b32_e32 v74, v154
	v_mov_b32_e32 v75, v154
	v_pk_mul_f32 v[76:77], v[74:75], v[76:77]
	v_lshl_add_u64 v[68:69], v[78:79], 0, v[0:1]
	v_cvt_pk_bf16_f32 v240, v80, v81
	v_cvt_pk_bf16_f32 v241, v76, v77
	s_nop 1
	v_mov_b64_e32 v[76:77], v[228:229]
	v_mov_b64_e32 v[78:79], v[230:231]
	v_mov_b32_e32 v67, v66
	v_pk_mul_f32 v[80:81], v[58:59], v[66:67]
	v_pk_mul_f32 v[76:77], v[80:81], v[76:77]
	v_pk_mul_f32 v[80:81], v[60:61], v[66:67]
	s_nop 0
	v_pk_mul_f32 v[78:79], v[80:81], v[78:79]
	s_and_saveexec_b64 s[0:1], vcc
	s_cbranch_execz .LBB0_1155
	s_waitcnt vmcnt(2)
	v_mov_b64_e32 v[80:81], v[196:197]
	v_mov_b64_e32 v[82:83], v[198:199]
	v_pk_mul_f32 v[86:87], v[76:77], v[80:81] op_sel:[1,1] op_sel_hi:[1,0]
	v_mul_f32_e32 v0, v79, v83
	v_pk_mul_f32 v[84:85], v[76:77], v[80:81]
	v_pk_fma_f32 v[76:77], v[76:77], v[80:81], v[86:87] op_sel_hi:[0,1,1]
	v_pk_fma_f32 v[80:81], v[78:79], v[82:83], v[0:1] op_sel_hi:[1,1,0] neg_lo:[0,0,1] neg_hi:[0,0,1]
	v_mul_f32_e32 v0, v79, v82
	v_pk_fma_f32 v[82:83], v[78:79], v[82:83], v[0:1] op_sel:[0,1,0] op_sel_hi:[1,0,0]
	v_sub_f32_e32 v76, v84, v86
	v_mov_b32_e32 v78, v80
	v_mov_b32_e32 v79, v82
.LBB0_1155:
	s_or_b64 exec, exec, s[0:1]
	v_pk_mul_f32 v[74:75], v[74:75], v[78:79]
	v_pk_mul_f32 v[76:77], v[154:155], v[76:77]
	v_pk_mul_f32 v[78:79], v[54:55], v[66:67]
	v_cvt_pk_bf16_f32 v242, v76, v77
	v_cvt_pk_bf16_f32 v243, v74, v75
	s_nop 1
	v_mov_b64_e32 v[74:75], v[232:233]
	v_mov_b64_e32 v[76:77], v[234:235]
	v_pk_mul_f32 v[74:75], v[78:79], v[74:75]
	v_pk_mul_f32 v[78:79], v[56:57], v[66:67]
	s_nop 0
	v_pk_mul_f32 v[78:79], v[78:79], v[76:77]
	s_and_saveexec_b64 s[0:1], vcc
	s_cbranch_execz .LBB0_1157
	s_waitcnt vmcnt(1)
	v_mov_b64_e32 v[80:81], v[200:201]
	v_mov_b64_e32 v[82:83], v[202:203]
	v_pk_mul_f32 v[84:85], v[74:75], v[80:81] op_sel:[1,1] op_sel_hi:[1,0]
	v_mul_f32_e32 v0, v79, v83
	v_pk_mul_f32 v[76:77], v[74:75], v[80:81]
	v_pk_fma_f32 v[74:75], v[74:75], v[80:81], v[84:85] op_sel_hi:[0,1,1]
	v_pk_fma_f32 v[80:81], v[78:79], v[82:83], v[0:1] op_sel_hi:[1,1,0] neg_lo:[0,0,1] neg_hi:[0,0,1]
	v_mul_f32_e32 v0, v79, v82
	v_pk_fma_f32 v[82:83], v[78:79], v[82:83], v[0:1] op_sel:[0,1,0] op_sel_hi:[1,0,0]
	v_sub_f32_e32 v74, v76, v84
	v_mov_b32_e32 v78, v80
	v_mov_b32_e32 v79, v82
.LBB0_1157:
	s_or_b64 exec, exec, s[0:1]
	v_mov_b32_e32 v76, v154
	v_mov_b32_e32 v77, v154
	v_pk_mul_f32 v[78:79], v[76:77], v[78:79]
	v_pk_mul_f32 v[74:75], v[154:155], v[74:75]
	v_pk_mul_f32 v[80:81], v[52:53], v[66:67]
	v_cvt_pk_bf16_f32 v244, v74, v75
	v_cvt_pk_bf16_f32 v245, v78, v79
	s_nop 1
	v_mov_b64_e32 v[72:73], v[236:237]
	v_mov_b64_e32 v[74:75], v[238:239]
	v_pk_mul_f32 v[78:79], v[50:51], v[66:67]
	v_pk_mul_f32 v[66:67], v[78:79], v[72:73]
	v_pk_mul_f32 v[72:73], v[80:81], v[74:75]
	s_and_saveexec_b64 s[0:1], vcc
	s_cbranch_execz .LBB0_1159
	s_waitcnt vmcnt(0)
	v_mov_b64_e32 v[78:79], v[204:205]
	v_mov_b64_e32 v[80:81], v[206:207]
	v_pk_mul_f32 v[82:83], v[66:67], v[78:79] op_sel:[1,1] op_sel_hi:[1,0]
	v_mul_f32_e32 v0, v73, v81
	v_pk_mul_f32 v[74:75], v[66:67], v[78:79]
	v_pk_fma_f32 v[66:67], v[66:67], v[78:79], v[82:83] op_sel_hi:[0,1,1]
	v_pk_fma_f32 v[78:79], v[72:73], v[80:81], v[0:1] op_sel_hi:[1,1,0] neg_lo:[0,0,1] neg_hi:[0,0,1]
	v_mul_f32_e32 v0, v73, v80
	v_pk_fma_f32 v[80:81], v[72:73], v[80:81], v[0:1] op_sel:[0,1,0] op_sel_hi:[1,0,0]
	v_sub_f32_e32 v66, v74, v82
	v_mov_b32_e32 v72, v78
	v_mov_b32_e32 v73, v80

.LBB0_1198:
	s_and_b64 vcc, exec, s[0:1]
	s_cbranch_vccz .LBB0_1208
	v_cmp_gt_i32_e32 vcc, s81, v54
	s_cbranch_vccz .Lrope_skip_5
	s_lshr_b32 s4, s28, 2
	s_and_b32 s4, s4, 0x7f0
	v_or_b32_e32 v55, s4, v167
	v_lshlrev_b32_e32 v55, 3, v55
	v_readlane_b32 s6, v254, 6
	v_readlane_b32 s7, v254, 7
	s_nop 4
	global_load_dwordx4 v[192:195], v55, s[6:7]
	global_load_dwordx4 v[196:199], v55, s[6:7] offset:64
	global_load_dwordx4 v[200:203], v[142:143], off
	global_load_dwordx4 v[204:207], v[142:143], off offset:64
.Lrope_skip_5:
	v_mul_f32_e32 v0, v47, v47
	v_fmac_f32_e32 v0, v46, v46
	v_fmac_f32_e32 v0, v48, v48
	v_fmac_f32_e32 v0, v49, v49
	v_fmac_f32_e32 v0, v42, v42
	v_fmac_f32_e32 v0, v43, v43
	v_fmac_f32_e32 v0, v44, v44
	v_fmac_f32_e32 v0, v45, v45
	v_fmac_f32_e32 v0, v38, v38
	v_fmac_f32_e32 v0, v39, v39
	v_pk_mul_f32 v[50:51], v[40:41], v[40:41]
	v_pk_mul_f32 v[52:53], v[34:35], v[34:35]
	v_add_f32_e32 v0, v50, v0
	v_add_f32_e32 v0, v51, v0
	v_add_f32_e32 v0, v52, v0
	v_pk_mul_f32 v[50:51], v[36:37], v[36:37]
	v_add_f32_e32 v0, v53, v0
	v_add_f32_e32 v0, v50, v0
	v_add_f32_e32 v0, v51, v0
	v_and_b32_e32 v51, 64, v214
	v_xor_b32_e32 v50, 16, v214
	v_add_u32_e32 v51, 64, v51
	v_cmp_lt_i32_e32 vcc, v50, v51
	s_and_b64 s[0:1], s[42:43], exec
	s_cselect_b32 s1, s18, s20
	v_cndmask_b32_e32 v50, v214, v50, vcc
	v_lshlrev_b32_e32 v50, 2, v50
	ds_bpermute_b32 v50, v50, v0
	s_cselect_b32 s0, s17, s19
	s_lshr_b32 s4, s28, 2
	s_and_b32 s4, s4, 0x7f0
	s_waitcnt lgkmcnt(0)
	v_add_f32_e32 v0, v0, v50
	v_xor_b32_e32 v50, 32, v214
	v_cmp_lt_i32_e32 vcc, v50, v51
	v_or_b32_e32 v51, s4, v167
	v_lshlrev_b32_e32 v55, 3, v51
	v_cndmask_b32_e32 v50, v214, v50, vcc
	v_lshlrev_b32_e32 v50, 2, v50
	ds_bpermute_b32 v50, v50, v0
	v_cmp_gt_i32_e32 vcc, s81, v54
	s_waitcnt lgkmcnt(0)
	v_add_f32_e32 v0, v0, v50
	v_fmamk_f32 v0, v0, 0x3c800000, v208
	v_rsq_f32_e32 v50, v0
	v_lshlrev_b32_e32 v0, 2, v138
	s_nop 1
	v_mov_b64_e32 v[56:57], v[224:225]
	v_mov_b64_e32 v[58:59], v[226:227]
	v_pk_mul_f32 v[52:53], v[46:47], v[50:51] op_sel_hi:[1,0]
	v_pk_mul_f32 v[52:53], v[56:57], v[52:53]
	v_pk_mul_f32 v[56:57], v[48:49], v[50:51] op_sel_hi:[1,0]
	s_nop 0
	v_pk_mul_f32 v[60:61], v[58:59], v[56:57]
	s_and_saveexec_b64 s[4:5], vcc
	s_cbranch_execz .LBB0_1201
	s_waitcnt vmcnt(3)
	v_mov_b64_e32 v[56:57], v[192:193]
	v_mov_b64_e32 v[58:59], v[194:195]
	v_pk_mul_f32 v[64:65], v[52:53], v[56:57] op_sel:[1,1] op_sel_hi:[1,0]
	v_pk_mul_f32 v[62:63], v[52:53], v[56:57]
	v_pk_fma_f32 v[52:53], v[52:53], v[56:57], v[64:65] op_sel_hi:[0,1,1]
	v_mul_f32_e32 v52, v61, v59
	v_pk_fma_f32 v[56:57], v[60:61], v[58:59], v[52:53] op_sel_hi:[1,1,0] neg_lo:[0,0,1] neg_hi:[0,0,1]
	v_mul_f32_e32 v52, v61, v58
	v_pk_fma_f32 v[58:59], v[60:61], v[58:59], v[52:53] op_sel:[0,1,0] op_sel_hi:[1,0,0]
	v_sub_f32_e32 v52, v62, v64
	v_mov_b32_e32 v60, v56
	v_mov_b32_e32 v61, v58
.LBB0_1201:
	s_or_b64 exec, exec, s[4:5]
	v_lshl_add_u64 v[56:57], s[0:1], 0, v[0:1]
	v_readlane_b32 s0, v254, 35
	v_readlane_b32 s1, v254, 36
	v_pk_mul_f32 v[64:65], v[154:155], v[52:53]
	v_lshlrev_b32_e32 v0, 1, v138
	v_mov_b64_e32 v[58:59], s[0:1]
	v_mad_i64_i32 v[58:59], s[0:1], v54, s52, v[58:59]
	s_lshl_b32 s0, s27, 1
	s_mov_b32 s1, s35
	v_lshl_add_u64 v[58:59], v[58:59], 0, s[0:1]
	v_lshl_add_u64 v[62:63], s[76:77], 1, v[58:59]
	v_mov_b32_e32 v58, v154
	v_mov_b32_e32 v59, v154
	v_pk_mul_f32 v[60:61], v[58:59], v[60:61]
	v_lshl_add_u64 v[52:53], v[62:63], 0, v[0:1]
	v_cvt_pk_bf16_f32 v240, v64, v65
	v_cvt_pk_bf16_f32 v241, v60, v61
	s_nop 1
	v_mov_b64_e32 v[60:61], v[228:229]
	v_mov_b64_e32 v[62:63], v[230:231]
	v_mov_b32_e32 v51, v50
	v_pk_mul_f32 v[64:65], v[42:43], v[50:51]
	v_pk_mul_f32 v[60:61], v[64:65], v[60:61]
	v_pk_mul_f32 v[64:65], v[44:45], v[50:51]
	s_nop 0
	v_pk_mul_f32 v[62:63], v[64:65], v[62:63]
	s_and_saveexec_b64 s[0:1], vcc
	s_cbranch_execz .LBB0_1203
	s_waitcnt vmcnt(2)
	v_mov_b64_e32 v[64:65], v[196:197]
	v_mov_b64_e32 v[66:67], v[198:199]
	v_pk_mul_f32 v[70:71], v[60:61], v[64:65] op_sel:[1,1] op_sel_hi:[1,0]
	v_mul_f32_e32 v0, v63, v67
	v_pk_mul_f32 v[68:69], v[60:61], v[64:65]
	v_pk_fma_f32 v[60:61], v[60:61], v[64:65], v[70:71] op_sel_hi:[0,1,1]
	v_pk_fma_f32 v[64:65], v[62:63], v[66:67], v[0:1] op_sel_hi:[1,1,0] neg_lo:[0,0,1] neg_hi:[0,0,1]
	v_mul_f32_e32 v0, v63, v66
	v_pk_fma_f32 v[66:67], v[62:63], v[66:67], v[0:1] op_sel:[0,1,0] op_sel_hi:[1,0,0]
	v_sub_f32_e32 v60, v68, v70
	v_mov_b32_e32 v62, v64
	v_mov_b32_e32 v63, v66
.LBB0_1203:
	s_or_b64 exec, exec, s[0:1]
	v_pk_mul_f32 v[58:59], v[58:59], v[62:63]
	v_pk_mul_f32 v[60:61], v[154:155], v[60:61]
	v_pk_mul_f32 v[62:63], v[38:39], v[50:51]
	v_cvt_pk_bf16_f32 v242, v60, v61
	v_cvt_pk_bf16_f32 v243, v58, v59
	s_nop 1
	v_mov_b64_e32 v[58:59], v[232:233]
	v_mov_b64_e32 v[60:61], v[234:235]
	v_pk_mul_f32 v[58:59], v[62:63], v[58:59]
	v_pk_mul_f32 v[62:63], v[40:41], v[50:51]
	s_nop 0
	v_pk_mul_f32 v[62:63], v[62:63], v[60:61]
	s_and_saveexec_b64 s[0:1], vcc
	s_cbranch_execz .LBB0_1205
	s_waitcnt vmcnt(1)
	v_mov_b64_e32 v[64:65], v[200:201]
	v_mov_b64_e32 v[66:67], v[202:203]
	v_pk_mul_f32 v[68:69], v[58:59], v[64:65] op_sel:[1,1] op_sel_hi:[1,0]
	v_mul_f32_e32 v0, v63, v67
	v_pk_mul_f32 v[60:61], v[58:59], v[64:65]
	v_pk_fma_f32 v[58:59], v[58:59], v[64:65], v[68:69] op_sel_hi:[0,1,1]
	v_pk_fma_f32 v[64:65], v[62:63], v[66:67], v[0:1] op_sel_hi:[1,1,0] neg_lo:[0,0,1] neg_hi:[0,0,1]
	v_mul_f32_e32 v0, v63, v66
	v_pk_fma_f32 v[66:67], v[62:63], v[66:67], v[0:1] op_sel:[0,1,0] op_sel_hi:[1,0,0]
	v_sub_f32_e32 v58, v60, v68
	v_mov_b32_e32 v62, v64
	v_mov_b32_e32 v63, v66
.LBB0_1205:
	s_or_b64 exec, exec, s[0:1]
	v_mov_b32_e32 v60, v154
	v_mov_b32_e32 v61, v154
	v_pk_mul_f32 v[62:63], v[60:61], v[62:63]
	v_pk_mul_f32 v[58:59], v[154:155], v[58:59]
	v_pk_mul_f32 v[64:65], v[36:37], v[50:51]
	v_cvt_pk_bf16_f32 v244, v58, v59
	v_cvt_pk_bf16_f32 v245, v62, v63
	s_nop 1
	v_mov_b64_e32 v[56:57], v[236:237]
	v_mov_b64_e32 v[58:59], v[238:239]
	v_pk_mul_f32 v[62:63], v[34:35], v[50:51]
	v_pk_mul_f32 v[50:51], v[62:63], v[56:57]
	v_pk_mul_f32 v[56:57], v[64:65], v[58:59]
	s_and_saveexec_b64 s[0:1], vcc
	s_cbranch_execz .LBB0_1207
	s_waitcnt vmcnt(0)
	v_mov_b64_e32 v[62:63], v[204:205]
	v_mov_b64_e32 v[64:65], v[206:207]
	v_pk_mul_f32 v[66:67], v[50:51], v[62:63] op_sel:[1,1] op_sel_hi:[1,0]
	v_mul_f32_e32 v0, v57, v65
	v_pk_mul_f32 v[58:59], v[50:51], v[62:63]
	v_pk_fma_f32 v[50:51], v[50:51], v[62:63], v[66:67] op_sel_hi:[0,1,1]
	v_pk_fma_f32 v[62:63], v[56:57], v[64:65], v[0:1] op_sel_hi:[1,1,0] neg_lo:[0,0,1] neg_hi:[0,0,1]
	v_mul_f32_e32 v0, v57, v64
	v_pk_fma_f32 v[64:65], v[56:57], v[64:65], v[0:1] op_sel:[0,1,0] op_sel_hi:[1,0,0]
	v_sub_f32_e32 v50, v58, v66
	v_mov_b32_e32 v56, v62
	v_mov_b32_e32 v57, v64

.LBB0_1246:
	s_and_b64 vcc, exec, s[0:1]
	s_cbranch_vccz .LBB0_1256
	v_cmp_gt_i32_e32 vcc, s81, v38
	s_cbranch_vccz .Lrope_skip_6
	s_lshr_b32 s4, s28, 2
	s_and_b32 s4, s4, 0x7f0
	v_or_b32_e32 v39, s4, v167
	v_lshlrev_b32_e32 v39, 3, v39
	v_readlane_b32 s6, v254, 6
	v_readlane_b32 s7, v254, 7
	s_nop 4
	global_load_dwordx4 v[192:195], v39, s[6:7]
	global_load_dwordx4 v[196:199], v39, s[6:7] offset:64
	global_load_dwordx4 v[200:203], v[144:145], off
	global_load_dwordx4 v[204:207], v[144:145], off offset:64
.Lrope_skip_6:
	v_mul_f32_e32 v0, v31, v31
	v_fmac_f32_e32 v0, v30, v30
	v_fmac_f32_e32 v0, v32, v32
	v_fmac_f32_e32 v0, v33, v33
	v_fmac_f32_e32 v0, v26, v26
	v_fmac_f32_e32 v0, v27, v27
	v_fmac_f32_e32 v0, v28, v28
	v_fmac_f32_e32 v0, v29, v29
	v_fmac_f32_e32 v0, v22, v22
	v_fmac_f32_e32 v0, v23, v23
	v_pk_mul_f32 v[34:35], v[24:25], v[24:25]
	v_pk_mul_f32 v[36:37], v[18:19], v[18:19]
	v_add_f32_e32 v0, v34, v0
	v_add_f32_e32 v0, v35, v0
	v_add_f32_e32 v0, v36, v0
	v_pk_mul_f32 v[34:35], v[20:21], v[20:21]
	v_add_f32_e32 v0, v37, v0
	v_add_f32_e32 v0, v34, v0
	v_add_f32_e32 v0, v35, v0
	v_and_b32_e32 v35, 64, v214
	v_xor_b32_e32 v34, 16, v214
	v_add_u32_e32 v35, 64, v35
	v_cmp_lt_i32_e32 vcc, v34, v35
	s_and_b64 s[0:1], s[42:43], exec
	s_cselect_b32 s1, s18, s20
	v_cndmask_b32_e32 v34, v214, v34, vcc
	v_lshlrev_b32_e32 v34, 2, v34
	ds_bpermute_b32 v34, v34, v0
	s_cselect_b32 s0, s17, s19
	s_lshr_b32 s4, s28, 2
	s_and_b32 s4, s4, 0x7f0
	s_waitcnt lgkmcnt(0)
	v_add_f32_e32 v0, v0, v34
	v_xor_b32_e32 v34, 32, v214
	v_cmp_lt_i32_e32 vcc, v34, v35
	v_or_b32_e32 v35, s4, v167
	v_lshlrev_b32_e32 v39, 3, v35
	v_cndmask_b32_e32 v34, v214, v34, vcc
	v_lshlrev_b32_e32 v34, 2, v34
	ds_bpermute_b32 v34, v34, v0
	v_cmp_gt_i32_e32 vcc, s81, v38
	s_waitcnt lgkmcnt(0)
	v_add_f32_e32 v0, v0, v34
	v_fmamk_f32 v0, v0, 0x3c800000, v208
	v_rsq_f32_e32 v34, v0
	v_lshlrev_b32_e32 v0, 2, v138
	s_nop 1
	v_mov_b64_e32 v[40:41], v[224:225]
	v_mov_b64_e32 v[42:43], v[226:227]
	v_pk_mul_f32 v[36:37], v[30:31], v[34:35] op_sel_hi:[1,0]
	v_pk_mul_f32 v[36:37], v[40:41], v[36:37]
	v_pk_mul_f32 v[40:41], v[32:33], v[34:35] op_sel_hi:[1,0]
	s_nop 0
	v_pk_mul_f32 v[44:45], v[42:43], v[40:41]
	s_and_saveexec_b64 s[4:5], vcc
	s_cbranch_execz .LBB0_1249
	s_waitcnt vmcnt(3)
	v_mov_b64_e32 v[40:41], v[192:193]
	v_mov_b64_e32 v[42:43], v[194:195]
	v_pk_mul_f32 v[48:49], v[36:37], v[40:41] op_sel:[1,1] op_sel_hi:[1,0]
	v_pk_mul_f32 v[46:47], v[36:37], v[40:41]
	v_pk_fma_f32 v[36:37], v[36:37], v[40:41], v[48:49] op_sel_hi:[0,1,1]
	v_mul_f32_e32 v36, v45, v43
	v_pk_fma_f32 v[40:41], v[44:45], v[42:43], v[36:37] op_sel_hi:[1,1,0] neg_lo:[0,0,1] neg_hi:[0,0,1]
	v_mul_f32_e32 v36, v45, v42
	v_pk_fma_f32 v[42:43], v[44:45], v[42:43], v[36:37] op_sel:[0,1,0] op_sel_hi:[1,0,0]
	v_sub_f32_e32 v36, v46, v48
	v_mov_b32_e32 v44, v40
	v_mov_b32_e32 v45, v42
.LBB0_1249:
	s_or_b64 exec, exec, s[4:5]
	v_lshl_add_u64 v[40:41], s[0:1], 0, v[0:1]
	v_readlane_b32 s0, v254, 35
	v_readlane_b32 s1, v254, 36
	v_pk_mul_f32 v[48:49], v[154:155], v[36:37]
	v_lshlrev_b32_e32 v0, 1, v138
	v_mov_b64_e32 v[42:43], s[0:1]
	v_mad_i64_i32 v[42:43], s[0:1], v38, s52, v[42:43]
	s_lshl_b32 s0, s27, 1
	s_mov_b32 s1, s35
	v_lshl_add_u64 v[42:43], v[42:43], 0, s[0:1]
	v_lshl_add_u64 v[46:47], s[76:77], 1, v[42:43]
	v_mov_b32_e32 v42, v154
	v_mov_b32_e32 v43, v154
	v_pk_mul_f32 v[44:45], v[42:43], v[44:45]
	v_lshl_add_u64 v[36:37], v[46:47], 0, v[0:1]
	v_cvt_pk_bf16_f32 v240, v48, v49
	v_cvt_pk_bf16_f32 v241, v44, v45
	s_nop 1
	v_mov_b64_e32 v[44:45], v[228:229]
	v_mov_b64_e32 v[46:47], v[230:231]
	v_mov_b32_e32 v35, v34
	v_pk_mul_f32 v[48:49], v[26:27], v[34:35]
	v_pk_mul_f32 v[44:45], v[48:49], v[44:45]
	v_pk_mul_f32 v[48:49], v[28:29], v[34:35]
	s_nop 0
	v_pk_mul_f32 v[46:47], v[48:49], v[46:47]
	s_and_saveexec_b64 s[0:1], vcc
	s_cbranch_execz .LBB0_1251
	s_waitcnt vmcnt(2)
	v_mov_b64_e32 v[48:49], v[196:197]
	v_mov_b64_e32 v[50:51], v[198:199]
	v_pk_mul_f32 v[54:55], v[44:45], v[48:49] op_sel:[1,1] op_sel_hi:[1,0]
	v_mul_f32_e32 v0, v47, v51
	v_pk_mul_f32 v[52:53], v[44:45], v[48:49]
	v_pk_fma_f32 v[44:45], v[44:45], v[48:49], v[54:55] op_sel_hi:[0,1,1]
	v_pk_fma_f32 v[48:49], v[46:47], v[50:51], v[0:1] op_sel_hi:[1,1,0] neg_lo:[0,0,1] neg_hi:[0,0,1]
	v_mul_f32_e32 v0, v47, v50
	v_pk_fma_f32 v[50:51], v[46:47], v[50:51], v[0:1] op_sel:[0,1,0] op_sel_hi:[1,0,0]
	v_sub_f32_e32 v44, v52, v54
	v_mov_b32_e32 v46, v48
	v_mov_b32_e32 v47, v50
.LBB0_1251:
	s_or_b64 exec, exec, s[0:1]
	v_pk_mul_f32 v[42:43], v[42:43], v[46:47]
	v_pk_mul_f32 v[44:45], v[154:155], v[44:45]
	v_pk_mul_f32 v[46:47], v[22:23], v[34:35]
	v_cvt_pk_bf16_f32 v242, v44, v45
	v_cvt_pk_bf16_f32 v243, v42, v43
	s_nop 1
	v_mov_b64_e32 v[42:43], v[232:233]
	v_mov_b64_e32 v[44:45], v[234:235]
	v_pk_mul_f32 v[42:43], v[46:47], v[42:43]
	v_pk_mul_f32 v[46:47], v[24:25], v[34:35]
	s_nop 0
	v_pk_mul_f32 v[46:47], v[46:47], v[44:45]
	s_and_saveexec_b64 s[0:1], vcc
	s_cbranch_execz .LBB0_1253
	s_waitcnt vmcnt(1)
	v_mov_b64_e32 v[48:49], v[200:201]
	v_mov_b64_e32 v[50:51], v[202:203]
	v_pk_mul_f32 v[52:53], v[42:43], v[48:49] op_sel:[1,1] op_sel_hi:[1,0]
	v_mul_f32_e32 v0, v47, v51
	v_pk_mul_f32 v[44:45], v[42:43], v[48:49]
	v_pk_fma_f32 v[42:43], v[42:43], v[48:49], v[52:53] op_sel_hi:[0,1,1]
	v_pk_fma_f32 v[48:49], v[46:47], v[50:51], v[0:1] op_sel_hi:[1,1,0] neg_lo:[0,0,1] neg_hi:[0,0,1]
	v_mul_f32_e32 v0, v47, v50
	v_pk_fma_f32 v[50:51], v[46:47], v[50:51], v[0:1] op_sel:[0,1,0] op_sel_hi:[1,0,0]
	v_sub_f32_e32 v42, v44, v52
	v_mov_b32_e32 v46, v48
	v_mov_b32_e32 v47, v50
.LBB0_1253:
	s_or_b64 exec, exec, s[0:1]
	v_mov_b32_e32 v44, v154
	v_mov_b32_e32 v45, v154
	v_pk_mul_f32 v[46:47], v[44:45], v[46:47]
	v_pk_mul_f32 v[42:43], v[154:155], v[42:43]
	v_pk_mul_f32 v[48:49], v[20:21], v[34:35]
	v_cvt_pk_bf16_f32 v244, v42, v43
	v_cvt_pk_bf16_f32 v245, v46, v47
	s_nop 1
	v_mov_b64_e32 v[40:41], v[236:237]
	v_mov_b64_e32 v[42:43], v[238:239]
	v_pk_mul_f32 v[46:47], v[18:19], v[34:35]
	v_pk_mul_f32 v[34:35], v[46:47], v[40:41]
	v_pk_mul_f32 v[40:41], v[48:49], v[42:43]
	s_and_saveexec_b64 s[0:1], vcc
	s_cbranch_execz .LBB0_1255
	s_waitcnt vmcnt(0)
	v_mov_b64_e32 v[46:47], v[204:205]
	v_mov_b64_e32 v[48:49], v[206:207]
	v_pk_mul_f32 v[50:51], v[34:35], v[46:47] op_sel:[1,1] op_sel_hi:[1,0]
	v_mul_f32_e32 v0, v41, v49
	v_pk_mul_f32 v[42:43], v[34:35], v[46:47]
	v_pk_fma_f32 v[34:35], v[34:35], v[46:47], v[50:51] op_sel_hi:[0,1,1]
	v_pk_fma_f32 v[46:47], v[40:41], v[48:49], v[0:1] op_sel_hi:[1,1,0] neg_lo:[0,0,1] neg_hi:[0,0,1]
	v_mul_f32_e32 v0, v41, v48
	v_pk_fma_f32 v[48:49], v[40:41], v[48:49], v[0:1] op_sel:[0,1,0] op_sel_hi:[1,0,0]
	v_sub_f32_e32 v34, v42, v50
	v_mov_b32_e32 v40, v46
	v_mov_b32_e32 v41, v48

.LBB0_1294:
	s_and_b64 vcc, exec, s[0:1]
	s_cbranch_vccz .LBB0_1304
	v_cmp_gt_i32_e32 vcc, s81, v22
	s_cbranch_vccz .Lrope_skip_7
	s_lshr_b32 s2, s28, 2
	s_and_b32 s2, s2, 0x7f0
	v_or_b32_e32 v23, s2, v167
	v_lshlrev_b32_e32 v23, 3, v23
	v_readlane_b32 s4, v254, 6
	v_readlane_b32 s5, v254, 7
	s_nop 4
	global_load_dwordx4 v[192:195], v23, s[4:5]
	global_load_dwordx4 v[196:199], v23, s[4:5] offset:64
	global_load_dwordx4 v[200:203], v[146:147], off
	global_load_dwordx4 v[204:207], v[146:147], off offset:64
.Lrope_skip_7:
	v_mul_f32_e32 v0, v15, v15
	v_fmac_f32_e32 v0, v14, v14
	v_fmac_f32_e32 v0, v16, v16
	v_fmac_f32_e32 v0, v17, v17
	v_fmac_f32_e32 v0, v10, v10
	v_fmac_f32_e32 v0, v11, v11
	v_fmac_f32_e32 v0, v12, v12
	v_fmac_f32_e32 v0, v13, v13
	v_fmac_f32_e32 v0, v6, v6
	v_fmac_f32_e32 v0, v7, v7
	v_pk_mul_f32 v[18:19], v[8:9], v[8:9]
	v_pk_mul_f32 v[20:21], v[2:3], v[2:3]
	v_add_f32_e32 v0, v18, v0
	v_add_f32_e32 v0, v19, v0
	v_add_f32_e32 v0, v20, v0
	v_pk_mul_f32 v[18:19], v[4:5], v[4:5]
	v_add_f32_e32 v0, v21, v0
	v_add_f32_e32 v0, v18, v0
	v_add_f32_e32 v0, v19, v0
	v_and_b32_e32 v19, 64, v214
	v_xor_b32_e32 v18, 16, v214
	v_add_u32_e32 v19, 64, v19
	v_cmp_lt_i32_e32 vcc, v18, v19
	s_and_b64 s[0:1], s[42:43], exec
	s_cselect_b32 s1, s18, s20
	v_cndmask_b32_e32 v18, v214, v18, vcc
	v_lshlrev_b32_e32 v18, 2, v18
	ds_bpermute_b32 v18, v18, v0
	s_cselect_b32 s0, s17, s19
	s_lshr_b32 s2, s28, 2
	s_and_b32 s2, s2, 0x7f0
	s_waitcnt lgkmcnt(0)
	v_add_f32_e32 v0, v0, v18
	v_xor_b32_e32 v18, 32, v214
	v_cmp_lt_i32_e32 vcc, v18, v19
	v_or_b32_e32 v19, s2, v167
	v_lshlrev_b32_e32 v23, 3, v19
	v_cndmask_b32_e32 v18, v214, v18, vcc
	v_lshlrev_b32_e32 v18, 2, v18
	ds_bpermute_b32 v18, v18, v0
	v_cmp_gt_i32_e32 vcc, s81, v22
	s_waitcnt lgkmcnt(0)
	v_add_f32_e32 v0, v0, v18
	v_fmamk_f32 v0, v0, 0x3c800000, v208
	v_rsq_f32_e32 v18, v0
	v_lshlrev_b32_e32 v0, 2, v138
	s_nop 1
	v_mov_b64_e32 v[24:25], v[224:225]
	v_mov_b64_e32 v[26:27], v[226:227]
	v_pk_mul_f32 v[20:21], v[14:15], v[18:19] op_sel_hi:[1,0]
	v_pk_mul_f32 v[20:21], v[24:25], v[20:21]
	v_pk_mul_f32 v[24:25], v[16:17], v[18:19] op_sel_hi:[1,0]
	s_nop 0
	v_pk_mul_f32 v[28:29], v[26:27], v[24:25]
	s_and_saveexec_b64 s[2:3], vcc
	s_cbranch_execz .LBB0_1297
	s_waitcnt vmcnt(3)
	v_mov_b64_e32 v[24:25], v[192:193]
	v_mov_b64_e32 v[26:27], v[194:195]
	v_pk_mul_f32 v[32:33], v[20:21], v[24:25] op_sel:[1,1] op_sel_hi:[1,0]
	v_pk_mul_f32 v[30:31], v[20:21], v[24:25]
	v_pk_fma_f32 v[20:21], v[20:21], v[24:25], v[32:33] op_sel_hi:[0,1,1]
	v_mul_f32_e32 v20, v29, v27
	v_pk_fma_f32 v[24:25], v[28:29], v[26:27], v[20:21] op_sel_hi:[1,1,0] neg_lo:[0,0,1] neg_hi:[0,0,1]
	v_mul_f32_e32 v20, v29, v26
	v_pk_fma_f32 v[26:27], v[28:29], v[26:27], v[20:21] op_sel:[0,1,0] op_sel_hi:[1,0,0]
	v_sub_f32_e32 v20, v30, v32
	v_mov_b32_e32 v28, v24
	v_mov_b32_e32 v29, v26
.LBB0_1297:
	s_or_b64 exec, exec, s[2:3]
	v_lshl_add_u64 v[24:25], s[0:1], 0, v[0:1]
	v_readlane_b32 s0, v254, 35
	v_readlane_b32 s1, v254, 36
	s_lshl_b32 s34, s27, 1
	v_pk_mul_f32 v[32:33], v[154:155], v[20:21]
	v_mov_b64_e32 v[26:27], s[0:1]
	v_mad_i64_i32 v[26:27], s[0:1], v22, s52, v[26:27]
	v_lshl_add_u64 v[26:27], v[26:27], 0, s[34:35]
	v_lshl_add_u64 v[30:31], s[76:77], 1, v[26:27]
	v_mov_b32_e32 v26, v154
	v_mov_b32_e32 v27, v154
	v_pk_mul_f32 v[28:29], v[26:27], v[28:29]
	v_lshlrev_b32_e32 v0, 1, v138
	v_lshl_add_u64 v[20:21], v[30:31], 0, v[0:1]
	v_cvt_pk_bf16_f32 v240, v32, v33
	v_cvt_pk_bf16_f32 v241, v28, v29
	s_nop 1
	v_mov_b64_e32 v[28:29], v[228:229]
	v_mov_b64_e32 v[30:31], v[230:231]
	v_mov_b32_e32 v19, v18
	v_pk_mul_f32 v[32:33], v[10:11], v[18:19]
	v_pk_mul_f32 v[28:29], v[32:33], v[28:29]
	v_pk_mul_f32 v[32:33], v[12:13], v[18:19]
	s_nop 0
	v_pk_mul_f32 v[30:31], v[32:33], v[30:31]
	s_and_saveexec_b64 s[0:1], vcc
	s_cbranch_execz .LBB0_1299
	s_waitcnt vmcnt(2)
	v_mov_b64_e32 v[32:33], v[196:197]
	v_mov_b64_e32 v[34:35], v[198:199]
	v_pk_mul_f32 v[38:39], v[28:29], v[32:33] op_sel:[1,1] op_sel_hi:[1,0]
	v_mul_f32_e32 v0, v31, v35
	v_pk_mul_f32 v[36:37], v[28:29], v[32:33]
	v_pk_fma_f32 v[28:29], v[28:29], v[32:33], v[38:39] op_sel_hi:[0,1,1]
	v_pk_fma_f32 v[32:33], v[30:31], v[34:35], v[0:1] op_sel_hi:[1,1,0] neg_lo:[0,0,1] neg_hi:[0,0,1]
	v_mul_f32_e32 v0, v31, v34
	v_pk_fma_f32 v[34:35], v[30:31], v[34:35], v[0:1] op_sel:[0,1,0] op_sel_hi:[1,0,0]
	v_sub_f32_e32 v28, v36, v38
	v_mov_b32_e32 v30, v32
	v_mov_b32_e32 v31, v34
.LBB0_1299:
	s_or_b64 exec, exec, s[0:1]
	v_pk_mul_f32 v[26:27], v[26:27], v[30:31]
	v_pk_mul_f32 v[28:29], v[154:155], v[28:29]
	v_pk_mul_f32 v[30:31], v[6:7], v[18:19]
	v_cvt_pk_bf16_f32 v242, v28, v29
	v_cvt_pk_bf16_f32 v243, v26, v27
	s_nop 1
	v_mov_b64_e32 v[26:27], v[232:233]
	v_mov_b64_e32 v[28:29], v[234:235]
	v_pk_mul_f32 v[26:27], v[30:31], v[26:27]
	v_pk_mul_f32 v[30:31], v[8:9], v[18:19]
	s_nop 0
	v_pk_mul_f32 v[30:31], v[30:31], v[28:29]
	s_and_saveexec_b64 s[0:1], vcc
	s_cbranch_execz .LBB0_1301
	s_waitcnt vmcnt(1)
	v_mov_b64_e32 v[32:33], v[200:201]
	v_mov_b64_e32 v[34:35], v[202:203]
	v_pk_mul_f32 v[36:37], v[26:27], v[32:33] op_sel:[1,1] op_sel_hi:[1,0]
	v_mul_f32_e32 v0, v31, v35
	v_pk_mul_f32 v[28:29], v[26:27], v[32:33]
	v_pk_fma_f32 v[26:27], v[26:27], v[32:33], v[36:37] op_sel_hi:[0,1,1]
	v_pk_fma_f32 v[32:33], v[30:31], v[34:35], v[0:1] op_sel_hi:[1,1,0] neg_lo:[0,0,1] neg_hi:[0,0,1]
	v_mul_f32_e32 v0, v31, v34
	v_pk_fma_f32 v[34:35], v[30:31], v[34:35], v[0:1] op_sel:[0,1,0] op_sel_hi:[1,0,0]
	v_sub_f32_e32 v26, v28, v36
	v_mov_b32_e32 v30, v32
	v_mov_b32_e32 v31, v34
.LBB0_1301:
	s_or_b64 exec, exec, s[0:1]
	v_mov_b32_e32 v28, v154
	v_mov_b32_e32 v29, v154
	v_pk_mul_f32 v[30:31], v[28:29], v[30:31]
	v_pk_mul_f32 v[26:27], v[154:155], v[26:27]
	v_pk_mul_f32 v[32:33], v[4:5], v[18:19]
	v_cvt_pk_bf16_f32 v244, v26, v27
	v_cvt_pk_bf16_f32 v245, v30, v31
	s_nop 1
	v_mov_b64_e32 v[24:25], v[236:237]
	v_mov_b64_e32 v[26:27], v[238:239]
	v_pk_mul_f32 v[30:31], v[2:3], v[18:19]
	v_pk_mul_f32 v[18:19], v[30:31], v[24:25]
	v_pk_mul_f32 v[24:25], v[32:33], v[26:27]
	s_and_saveexec_b64 s[0:1], vcc
	s_cbranch_execz .LBB0_1303
	s_waitcnt vmcnt(0)
	v_mov_b64_e32 v[30:31], v[204:205]
	v_mov_b64_e32 v[32:33], v[206:207]
	v_pk_mul_f32 v[34:35], v[18:19], v[30:31] op_sel:[1,1] op_sel_hi:[1,0]
	v_mul_f32_e32 v0, v25, v33
	v_pk_mul_f32 v[26:27], v[18:19], v[30:31]
	v_pk_fma_f32 v[18:19], v[18:19], v[30:31], v[34:35] op_sel_hi:[0,1,1]
	v_pk_fma_f32 v[30:31], v[24:25], v[32:33], v[0:1] op_sel_hi:[1,1,0] neg_lo:[0,0,1] neg_hi:[0,0,1]
	v_mul_f32_e32 v0, v25, v32
	v_pk_fma_f32 v[32:33], v[24:25], v[32:33], v[0:1] op_sel:[0,1,0] op_sel_hi:[1,0,0]
	v_sub_f32_e32 v18, v26, v34
	v_mov_b32_e32 v24, v30
	v_mov_b32_e32 v25, v32
